# flat to global memory ops; first K-iteration peeled with srcC=0 instead of zeroing accumulators (swiglu, resid, mixin GEMMs); 64-bit zeroing elsewhere
# speedup vs baseline: 1.0153x; 1.0085x over previous
.LBB0_256:
	v_mov_b32_e32 v0, 0
	s_add_i32 s0, s98, -2
	s_mov_b64 s[38:39], 0
	s_mov_b32 s43, 0
	v_mov_b32_e32 v1, v0
	v_mov_b32_e32 v2, v0
	v_mov_b32_e32 v3, v0
	v_mov_b32_e32 v4, v0
	v_mov_b32_e32 v5, v0
	v_mov_b32_e32 v6, v0
	v_mov_b32_e32 v7, v0
	v_mov_b32_e32 v12, v0
	s_waitcnt lgkmcnt(0)
	v_mov_b64_e32 v[8:9], 0
	v_mov_b64_e32 v[10:11], 0
	v_mov_b32_e32 v13, 0
	v_mov_b64_e32 v[14:15], 0
	v_mov_b64_e32 v[16:17], 0
	v_mov_b64_e32 v[18:19], 0
	v_mov_b64_e32 v[20:21], 0
	v_mov_b64_e32 v[22:23], 0
	v_mov_b64_e32 v[24:25], 0
	v_mov_b64_e32 v[26:27], 0
	v_mov_b64_e32 v[28:29], 0
	v_mov_b64_e32 v[30:31], 0
	v_mov_b64_e32 v[32:33], 0
	v_mov_b64_e32 v[34:35], 0
	v_mov_b64_e32 v[36:37], 0
	v_mov_b64_e32 v[38:39], 0
	v_mov_b64_e32 v[40:41], 0
	v_mov_b64_e32 v[42:43], 0
	v_mov_b64_e32 v[44:45], 0
	v_mov_b64_e32 v[46:47], 0
	v_mov_b64_e32 v[48:49], 0
	v_mov_b64_e32 v[50:51], 0
	v_mov_b64_e32 v[52:53], 0
	v_mov_b64_e32 v[54:55], 0
	v_mov_b64_e32 v[56:57], 0
	v_mov_b64_e32 v[58:59], 0
	v_mov_b64_e32 v[60:61], 0
	v_mov_b64_e32 v[62:63], 0
	v_mov_b64_e32 v[64:65], 0
	v_mov_b64_e32 v[66:67], 0
	v_mov_b64_e32 v[68:69], 0
	v_mov_b64_e32 v[70:71], 0
	v_mov_b64_e32 v[72:73], 0
	v_mov_b64_e32 v[74:75], 0
	v_mov_b64_e32 v[76:77], 0
	v_mov_b64_e32 v[78:79], 0
	v_mov_b64_e32 v[80:81], 0
	v_mov_b64_e32 v[82:83], 0
	v_mov_b64_e32 v[84:85], 0
	v_mov_b64_e32 v[86:87], 0
	v_mov_b64_e32 v[88:89], 0
	v_mov_b64_e32 v[90:91], 0
	v_mov_b64_e32 v[92:93], 0
	v_mov_b64_e32 v[94:95], 0
	v_mov_b64_e32 v[96:97], 0
	v_mov_b64_e32 v[98:99], 0
	v_mov_b64_e32 v[100:101], 0
	v_mov_b64_e32 v[102:103], 0
	v_mov_b64_e32 v[104:105], 0
	v_mov_b64_e32 v[106:107], 0
	v_mov_b64_e32 v[108:109], 0
	v_mov_b64_e32 v[110:111], 0
	v_mov_b64_e32 v[112:113], 0
	v_mov_b64_e32 v[114:115], 0
	v_mov_b64_e32 v[116:117], 0
	v_mov_b64_e32 v[118:119], 0
	v_mov_b64_e32 v[120:121], 0
	v_mov_b64_e32 v[122:123], 0
	v_mov_b64_e32 v[124:125], 0
	v_mov_b64_e32 v[126:127], 0

.LBB0_270:
	s_add_i32 s54, s54, 1
	s_mul_i32 s4, s54, s70
	s_mov_b32 s3, s87
	s_add_i32 s87, s4, s88
	s_mov_b32 s0, s89
	s_ashr_i32 s89, s87, 7
	s_cmpk_lt_i32 s87, 0x200
	s_cselect_b64 s[34:35], -1, 0
	s_and_b64 s[4:5], s[34:35], exec
	s_cselect_b32 s28, s89, s0
	s_cselect_b32 s4, s87, s3
	s_ashr_i32 s29, s28, 31
	s_lshl_b64 s[28:29], s[28:29], 17
	s_add_u32 s28, s14, s28
	s_addc_u32 s29, s15, s29
	s_ashr_i32 s5, s4, 31
	s_lshl_b64 s[4:5], s[4:5], 17
	s_add_u32 s30, s56, s4
	v_mov_b32_e32 v123, 0
	s_addc_u32 s31, s57, s5
	s_andn2_b64 vcc, exec, s[24:25]
	v_mov_b32_e32 v122, v123
	v_mov_b32_e32 v121, v123
	v_mov_b32_e32 v120, v123
	v_mov_b32_e32 v127, v123
	v_mov_b32_e32 v126, v123
	v_mov_b32_e32 v125, v123
	v_mov_b32_e32 v124, v123
	v_mov_b32_e32 v111, v123
	v_mov_b32_e32 v110, v123
	v_mov_b32_e32 v109, v123
	v_mov_b32_e32 v108, v123
	v_mov_b32_e32 v107, v123
	v_mov_b32_e32 v106, v123
	v_mov_b32_e32 v105, v123
	v_mov_b32_e32 v104, v123
	v_mov_b32_e32 v95, v123
	v_mov_b32_e32 v94, v123
	v_mov_b32_e32 v93, v123
	v_mov_b32_e32 v92, v123
	v_mov_b32_e32 v91, v123
	v_mov_b32_e32 v90, v123
	v_mov_b32_e32 v89, v123
	v_mov_b32_e32 v88, v123
	v_mov_b32_e32 v79, v123
	v_mov_b32_e32 v78, v123
	v_mov_b32_e32 v77, v123
	v_mov_b32_e32 v76, v123
	v_mov_b32_e32 v75, v123
	v_mov_b32_e32 v74, v123
	v_mov_b32_e32 v73, v123
	v_mov_b32_e32 v72, v123
	v_mov_b32_e32 v119, v123
	v_mov_b32_e32 v118, v123
	v_mov_b32_e32 v117, v123
	v_mov_b32_e32 v116, v123
	v_mov_b32_e32 v115, v123
	v_mov_b32_e32 v114, v123
	v_mov_b32_e32 v113, v123
	v_mov_b32_e32 v112, v123
	v_mov_b32_e32 v103, v123
	v_mov_b32_e32 v102, v123
	v_mov_b32_e32 v101, v123
	v_mov_b32_e32 v100, v123
	v_mov_b32_e32 v99, v123
	v_mov_b32_e32 v98, v123
	v_mov_b32_e32 v97, v123
	v_mov_b32_e32 v96, v123
	v_mov_b32_e32 v87, v123
	v_mov_b32_e32 v86, v123
	v_mov_b32_e32 v85, v123
	v_mov_b32_e32 v84, v123
	v_mov_b32_e32 v83, v123
	v_mov_b32_e32 v82, v123
	v_mov_b32_e32 v81, v123
	v_mov_b32_e32 v80, v123
	v_mov_b32_e32 v71, v123
	v_mov_b32_e32 v70, v123
	v_mov_b32_e32 v69, v123
	v_mov_b32_e32 v68, v123
	v_mov_b32_e32 v67, v123
	v_mov_b32_e32 v66, v123
	v_mov_b32_e32 v65, v123
	v_mov_b32_e32 v64, v123
	v_mov_b32_e32 v63, v123
	v_mov_b32_e32 v62, v123
	v_mov_b32_e32 v61, v123
	v_mov_b32_e32 v60, v123
	v_mov_b32_e32 v59, v123
	v_mov_b32_e32 v58, v123
	v_mov_b32_e32 v57, v123
	v_mov_b32_e32 v56, v123
	v_mov_b32_e32 v47, v123
	v_mov_b32_e32 v46, v123
	v_mov_b32_e32 v45, v123
	v_mov_b32_e32 v44, v123
	v_mov_b32_e32 v43, v123
	v_mov_b32_e32 v42, v123
	v_mov_b32_e32 v41, v123
	v_mov_b32_e32 v40, v123
	v_mov_b32_e32 v31, v123
	v_mov_b32_e32 v30, v123
	v_mov_b32_e32 v29, v123
	v_mov_b32_e32 v28, v123
	v_mov_b32_e32 v27, v123
	v_mov_b32_e32 v26, v123
	v_mov_b32_e32 v25, v123
	v_mov_b32_e32 v24, v123
	v_mov_b32_e32 v15, v123
	v_mov_b32_e32 v14, v123
	v_mov_b32_e32 v13, v123
	v_mov_b32_e32 v12, v123
	v_mov_b32_e32 v11, v123
	v_mov_b32_e32 v10, v123
	v_mov_b32_e32 v9, v123
	v_mov_b32_e32 v8, v123
	v_mov_b32_e32 v55, v123
	v_mov_b32_e32 v54, v123
	v_mov_b32_e32 v53, v123
	v_mov_b32_e32 v52, v123
	v_mov_b32_e32 v51, v123
	v_mov_b32_e32 v50, v123
	v_mov_b32_e32 v49, v123
	v_mov_b32_e32 v48, v123
	v_mov_b32_e32 v39, v123
	v_mov_b32_e32 v38, v123
	v_mov_b32_e32 v37, v123
	v_mov_b32_e32 v36, v123
	v_mov_b32_e32 v35, v123
	v_mov_b32_e32 v34, v123
	v_mov_b32_e32 v33, v123
	v_mov_b32_e32 v32, v123
	v_mov_b32_e32 v23, v123
	v_mov_b32_e32 v22, v123
	v_mov_b32_e32 v21, v123
	v_mov_b32_e32 v20, v123
	v_mov_b32_e32 v19, v123
	v_mov_b32_e32 v18, v123
	v_mov_b32_e32 v17, v123
	v_mov_b32_e32 v16, v123
	v_mov_b32_e32 v7, v123
	v_mov_b32_e32 v6, v123
	v_mov_b32_e32 v5, v123
	v_mov_b32_e32 v4, v123
	v_mov_b32_e32 v3, v123
	v_mov_b32_e32 v2, v123
	v_mov_b32_e32 v1, v123
	v_mov_b32_e32 v0, v123
	s_cbranch_vccnz .LBB0_273
	s_and_b64 s[4:5], s[34:35], exec
	v_mov_b32_e32 v0, 0
	s_cselect_b32 s39, s29, s97
	s_cselect_b32 s91, s28, s96
	s_cselect_b32 s4, s31, s95
	s_cselect_b32 s5, s30, s94
	s_mov_b64 s[36:37], 0
	s_mov_b32 s0, 0
	v_mov_b32_e32 v1, 0
	v_mov_b64_e32 v[2:3], 0
	v_mov_b64_e32 v[4:5], 0
	v_mov_b64_e32 v[6:7], 0
	v_mov_b64_e32 v[8:9], 0
	v_mov_b64_e32 v[10:11], 0
	v_mov_b64_e32 v[12:13], 0
	v_mov_b64_e32 v[14:15], 0
	v_mov_b64_e32 v[16:17], 0
	v_mov_b64_e32 v[18:19], 0
	v_mov_b64_e32 v[20:21], 0
	v_mov_b64_e32 v[22:23], 0
	v_mov_b64_e32 v[24:25], 0
	v_mov_b64_e32 v[26:27], 0
	v_mov_b64_e32 v[28:29], 0
	v_mov_b64_e32 v[30:31], 0
	v_mov_b64_e32 v[32:33], 0
	v_mov_b64_e32 v[34:35], 0
	v_mov_b64_e32 v[36:37], 0
	v_mov_b64_e32 v[38:39], 0
	v_mov_b64_e32 v[40:41], 0
	v_mov_b64_e32 v[42:43], 0
	v_mov_b64_e32 v[44:45], 0
	v_mov_b64_e32 v[46:47], 0
	v_mov_b64_e32 v[48:49], 0
	v_mov_b64_e32 v[50:51], 0
	v_mov_b64_e32 v[52:53], 0
	v_mov_b64_e32 v[54:55], 0
	v_mov_b64_e32 v[56:57], 0
	v_mov_b64_e32 v[58:59], 0
	v_mov_b64_e32 v[60:61], 0
	v_mov_b64_e32 v[62:63], 0
	v_mov_b64_e32 v[64:65], 0
	v_mov_b64_e32 v[66:67], 0
	v_mov_b64_e32 v[68:69], 0
	v_mov_b64_e32 v[70:71], 0
	v_mov_b64_e32 v[72:73], 0
	v_mov_b64_e32 v[74:75], 0
	v_mov_b64_e32 v[76:77], 0
	v_mov_b64_e32 v[78:79], 0
	v_mov_b64_e32 v[80:81], 0
	v_mov_b64_e32 v[82:83], 0
	v_mov_b64_e32 v[84:85], 0
	v_mov_b64_e32 v[86:87], 0
	v_mov_b64_e32 v[88:89], 0
	v_mov_b64_e32 v[90:91], 0
	v_mov_b64_e32 v[92:93], 0
	v_mov_b64_e32 v[94:95], 0
	v_mov_b64_e32 v[96:97], 0
	v_mov_b64_e32 v[98:99], 0
	v_mov_b64_e32 v[100:101], 0
	v_mov_b64_e32 v[102:103], 0
	v_mov_b64_e32 v[104:105], 0
	v_mov_b64_e32 v[106:107], 0
	v_mov_b64_e32 v[108:109], 0
	v_mov_b64_e32 v[110:111], 0
	v_mov_b64_e32 v[112:113], 0
	v_mov_b64_e32 v[114:115], 0
	v_mov_b64_e32 v[116:117], 0
	v_mov_b64_e32 v[118:119], 0
	v_mov_b64_e32 v[120:121], 0
	v_mov_b64_e32 v[122:123], 0
	v_mov_b64_e32 v[124:125], 0
	v_mov_b64_e32 v[126:127], 0

.LBB0_328:
	s_ashr_i32 s31, s30, 31
	s_lshl_b64 s[34:35], s[30:31], 19
	s_add_u32 s34, s84, s34
	s_addc_u32 s35, s85, s35
	s_and_b64 s[38:39], s[4:5], exec
	s_cselect_b32 s7, s35, s93
	s_cselect_b32 s11, s34, s92
	s_ashr_i32 s29, s28, 31
	s_lshl_b64 s[38:39], s[28:29], 19
	s_add_u32 s38, s56, s38
	s_addc_u32 s39, s57, s39
	s_and_b64 s[46:47], s[4:5], exec
	s_cselect_b32 s0, s39, s37
	s_cselect_b32 s29, s38, s36
	s_mov_b64 s[46:47], 0
	s_mov_b32 s31, -2
	s_add_u32 s50, s46, 0x100
	s_addc_u32 s51, s47, 0
	s_add_u32 s3, s46, 0xfffff900
	v_cmp_gt_u64_e32 vcc, s[50:51], v[192:193]
	s_addc_u32 s33, s47, -1
	s_and_b64 s[76:77], vcc, exec
	s_cselect_b32 s50, s3, s50
	s_cselect_b32 s51, s33, s51
	s_add_u32 s3, s92, s50
	s_addc_u32 s33, s93, s51
	s_add_u32 s43, s36, s50
	s_addc_u32 s54, s37, s51
	s_add_i32 s69, 0, 0x10000
	s_cmp_eq_u32 s31, 12
	s_cselect_b32 s97, s7, s33
	s_cselect_b32 s96, s11, s3
	s_cselect_b32 s95, s0, s54
	s_cselect_b32 s94, s29, s43
	s_add_i32 s3, 0, 0x14000
	v_add_u32_e32 v100, s69, v184
	v_add_u32_e32 v168, s3, v184
	ds_read_b128 v[40:43], v100
	ds_read_b128 v[60:63], v100 offset:1024
	ds_read_b128 v[80:83], v100 offset:2048
	ds_read_b128 v[100:103], v100 offset:3072
	ds_read_b128 v[120:123], v168
	ds_read_b128 v[140:143], v168 offset:1024
	ds_read_b128 v[152:155], v168 offset:2048
	ds_read_b128 v[168:171], v168 offset:3072
	s_add_u32 s33, s92, s46
	s_addc_u32 s43, s93, s47
	s_add_u32 s46, s33, 0x40080
	s_addc_u32 s47, s43, 0
	v_lshl_add_u64 v[224:225], s[46:47], 0, v[156:157]
	s_add_i32 m0, s23, 0xc000
	ds_read_b128 v[172:175], v202
	ds_read_b128 v[176:179], v202 offset:1024
	ds_read_b128 v[180:183], v202 offset:2048
	ds_read_b128 v[204:207], v202 offset:3072
	ds_read_b128 v[208:211], v202 offset:4096
	ds_read_b128 v[212:215], v202 offset:5120
	ds_read_b128 v[216:219], v202 offset:6144
	ds_read_b128 v[220:223], v202 offset:7168
	global_load_lds_dwordx4 v[224:225], off
	v_lshl_add_u64 v[224:225], s[46:47], 0, v[160:161]
	s_add_i32 m0, s23, 0xe000
	s_nop 0
	global_load_lds_dwordx4 v[224:225], off
	s_waitcnt vmcnt(8)
	s_waitcnt lgkmcnt(0)
	s_barrier
	s_setprio 1
	s_waitcnt lgkmcnt(0)
	v_mfma_f32_16x16x32_bf16 v[148:151], v[40:43], v[172:175], 0
	v_mfma_f32_16x16x32_bf16 v[144:147], v[80:83], v[172:175], 0
	v_mfma_f32_16x16x32_bf16 v[128:131], v[40:43], v[180:183], 0
	v_mfma_f32_16x16x32_bf16 v[124:127], v[80:83], v[180:183], 0
	v_mfma_f32_16x16x32_bf16 v[108:111], v[40:43], v[208:211], 0
	v_mfma_f32_16x16x32_bf16 v[104:107], v[80:83], v[208:211], 0
	v_mfma_f32_16x16x32_bf16 v[88:91], v[40:43], v[216:219], 0
	v_mfma_f32_16x16x32_bf16 v[84:87], v[80:83], v[216:219], 0
	v_mfma_f32_16x16x32_bf16 v[148:151], v[60:63], v[176:179], v[148:151]
	v_mfma_f32_16x16x32_bf16 v[144:147], v[100:103], v[176:179], v[144:147]
	v_mfma_f32_16x16x32_bf16 v[128:131], v[60:63], v[204:207], v[128:131]
	v_mfma_f32_16x16x32_bf16 v[124:127], v[100:103], v[204:207], v[124:127]
	v_mfma_f32_16x16x32_bf16 v[108:111], v[60:63], v[212:215], v[108:111]
	v_mfma_f32_16x16x32_bf16 v[104:107], v[100:103], v[212:215], v[104:107]
	v_mfma_f32_16x16x32_bf16 v[88:91], v[60:63], v[220:223], v[88:91]
	v_mfma_f32_16x16x32_bf16 v[84:87], v[100:103], v[220:223], v[84:87]
	s_setprio 0
	s_setprio 1
	v_mfma_f32_16x16x32_bf16 v[136:139], v[120:123], v[172:175], 0
	v_mfma_f32_16x16x32_bf16 v[132:135], v[152:155], v[172:175], 0
	v_mfma_f32_16x16x32_bf16 v[116:119], v[120:123], v[180:183], 0
	v_mfma_f32_16x16x32_bf16 v[112:115], v[152:155], v[180:183], 0
	v_mfma_f32_16x16x32_bf16 v[96:99], v[120:123], v[208:211], 0
	v_mfma_f32_16x16x32_bf16 v[92:95], v[152:155], v[208:211], 0
	v_mfma_f32_16x16x32_bf16 v[76:79], v[120:123], v[216:219], 0
	v_mfma_f32_16x16x32_bf16 v[72:75], v[152:155], v[216:219], 0
	v_mfma_f32_16x16x32_bf16 v[136:139], v[140:143], v[176:179], v[136:139]
	v_mfma_f32_16x16x32_bf16 v[132:135], v[168:171], v[176:179], v[132:135]
	v_mfma_f32_16x16x32_bf16 v[116:119], v[140:143], v[204:207], v[116:119]
	v_mfma_f32_16x16x32_bf16 v[112:115], v[168:171], v[204:207], v[112:115]
	v_mfma_f32_16x16x32_bf16 v[96:99], v[140:143], v[212:215], v[96:99]
	v_mfma_f32_16x16x32_bf16 v[92:95], v[168:171], v[212:215], v[92:95]
	v_mfma_f32_16x16x32_bf16 v[76:79], v[140:143], v[220:223], v[76:79]
	v_mfma_f32_16x16x32_bf16 v[72:75], v[168:171], v[220:223], v[72:75]
	s_setprio 0
	s_barrier
	s_add_i32 s33, s69, s60
	v_lshl_add_u64 v[224:225], s[94:95], 0, v[158:159]
	s_mov_b32 m0, s33
	ds_read_b128 v[172:175], v202 offset:16384
	ds_read_b128 v[176:179], v202 offset:17408
	ds_read_b128 v[180:183], v202 offset:18432
	ds_read_b128 v[204:207], v202 offset:19456
	ds_read_b128 v[208:211], v202 offset:20480
	ds_read_b128 v[212:215], v202 offset:21504
	ds_read_b128 v[216:219], v202 offset:22528
	ds_read_b128 v[220:223], v202 offset:23552
	global_load_lds_dwordx4 v[224:225], off
	s_add_i32 m0, s33, 0x2000
	s_add_u32 s46, s94, 0x40000
	v_lshl_add_u64 v[226:227], s[94:95], 0, v[162:163]
	s_addc_u32 s47, s95, 0
	s_add_i32 s3, s3, s60
	global_load_lds_dwordx4 v[226:227], off
	v_lshl_add_u64 v[234:235], s[46:47], 0, v[158:159]
	s_mov_b32 m0, s3
	v_lshl_add_u64 v[236:237], s[96:97], 0, v[160:161]
	global_load_lds_dwordx4 v[234:235], off
	v_lshl_add_u64 v[234:235], s[46:47], 0, v[162:163]
	s_add_i32 m0, s3, 0x2000
	s_nop 0
	global_load_lds_dwordx4 v[234:235], off
	v_lshl_add_u64 v[234:235], s[96:97], 0, v[156:157]
	s_mov_b32 m0, s23
	s_nop 0
	global_load_lds_dwordx4 v[234:235], off
	s_mov_b32 m0, s87
	s_nop 0
	global_load_lds_dwordx4 v[236:237], off
	s_waitcnt vmcnt(8)
	s_waitcnt lgkmcnt(0)
	s_barrier
	s_setprio 1
	s_waitcnt lgkmcnt(0)
	v_mfma_f32_16x16x32_bf16 v[68:71], v[40:43], v[172:175], 0
	v_mfma_f32_16x16x32_bf16 v[64:67], v[80:83], v[172:175], 0
	v_mfma_f32_16x16x32_bf16 v[48:51], v[40:43], v[180:183], 0
	v_mfma_f32_16x16x32_bf16 v[44:47], v[80:83], v[180:183], 0
	v_mfma_f32_16x16x32_bf16 v[28:31], v[40:43], v[208:211], 0
	v_mfma_f32_16x16x32_bf16 v[24:27], v[80:83], v[208:211], 0
	v_mfma_f32_16x16x32_bf16 v[12:15], v[40:43], v[216:219], 0
	v_mfma_f32_16x16x32_bf16 v[8:11], v[80:83], v[216:219], 0
	v_mfma_f32_16x16x32_bf16 v[68:71], v[60:63], v[176:179], v[68:71]
	v_mfma_f32_16x16x32_bf16 v[64:67], v[100:103], v[176:179], v[64:67]
	v_mfma_f32_16x16x32_bf16 v[48:51], v[60:63], v[204:207], v[48:51]
	v_mfma_f32_16x16x32_bf16 v[44:47], v[100:103], v[204:207], v[44:47]
	v_mfma_f32_16x16x32_bf16 v[28:31], v[60:63], v[212:215], v[28:31]
	v_mfma_f32_16x16x32_bf16 v[24:27], v[100:103], v[212:215], v[24:27]
	v_mfma_f32_16x16x32_bf16 v[12:15], v[60:63], v[220:223], v[12:15]
	v_mfma_f32_16x16x32_bf16 v[8:11], v[100:103], v[220:223], v[8:11]
	s_setprio 0
	s_setprio 1
	v_mfma_f32_16x16x32_bf16 v[52:55], v[152:155], v[172:175], 0
	v_mfma_f32_16x16x32_bf16 v[36:39], v[120:123], v[180:183], 0
	v_mfma_f32_16x16x32_bf16 v[32:35], v[152:155], v[180:183], 0
	v_mfma_f32_16x16x32_bf16 v[20:23], v[120:123], v[208:211], 0
	v_mfma_f32_16x16x32_bf16 v[16:19], v[152:155], v[208:211], 0
	v_mfma_f32_16x16x32_bf16 v[4:7], v[120:123], v[216:219], 0
	v_mfma_f32_16x16x32_bf16 v[0:3], v[152:155], v[216:219], 0
	v_mfma_f32_16x16x32_bf16 v[40:43], v[120:123], v[172:175], 0
	v_mfma_f32_16x16x32_bf16 v[52:55], v[168:171], v[176:179], v[52:55]
	v_mfma_f32_16x16x32_bf16 v[36:39], v[140:143], v[204:207], v[36:39]
	v_mfma_f32_16x16x32_bf16 v[32:35], v[168:171], v[204:207], v[32:35]
	v_mfma_f32_16x16x32_bf16 v[20:23], v[140:143], v[212:215], v[20:23]
	v_mfma_f32_16x16x32_bf16 v[16:19], v[168:171], v[212:215], v[16:19]
	v_mfma_f32_16x16x32_bf16 v[4:7], v[140:143], v[220:223], v[4:7]
	v_mfma_f32_16x16x32_bf16 v[0:3], v[168:171], v[220:223], v[0:3]
	v_mfma_f32_16x16x32_bf16 v[40:43], v[140:143], v[176:179], v[40:43]
	s_setprio 0
	s_barrier
	s_add_i32 s3, 0, 0x18000
	s_add_i32 s33, 0, 0x1c000
	v_add_u32_e32 v100, s3, v184
	v_add_u32_e32 v168, s33, v184
	ds_read_b128 v[56:59], v100
	ds_read_b128 v[60:63], v100 offset:1024
	ds_read_b128 v[80:83], v100 offset:2048
	ds_read_b128 v[100:103], v100 offset:3072
	ds_read_b128 v[120:123], v168
	ds_read_b128 v[140:143], v168 offset:1024
	ds_read_b128 v[152:155], v168 offset:2048
	ds_read_b128 v[168:171], v168 offset:3072
	s_add_u32 s46, s96, 0x40000
	s_addc_u32 s47, s97, 0
	s_mov_b32 m0, s89
	v_lshl_add_u64 v[238:239], s[46:47], 0, v[156:157]
	ds_read_b128 v[172:175], v202 offset:32768
	ds_read_b128 v[176:179], v202 offset:33792
	ds_read_b128 v[180:183], v202 offset:34816
	ds_read_b128 v[204:207], v202 offset:35840
	ds_read_b128 v[208:211], v202 offset:36864
	ds_read_b128 v[212:215], v202 offset:37888
	ds_read_b128 v[216:219], v202 offset:38912
	ds_read_b128 v[220:223], v202 offset:39936
	global_load_lds_dwordx4 v[238:239], off
	v_lshl_add_u64 v[238:239], s[46:47], 0, v[160:161]
	s_mov_b32 m0, s98
	s_nop 0
	global_load_lds_dwordx4 v[238:239], off
	s_waitcnt vmcnt(8)
	s_waitcnt lgkmcnt(0)
	s_barrier
	s_setprio 1
	s_waitcnt lgkmcnt(0)
	v_mfma_f32_16x16x32_bf16 v[148:151], v[56:59], v[172:175], v[148:151]
	v_mfma_f32_16x16x32_bf16 v[144:147], v[80:83], v[172:175], v[144:147]
	v_mfma_f32_16x16x32_bf16 v[128:131], v[56:59], v[180:183], v[128:131]
	v_mfma_f32_16x16x32_bf16 v[124:127], v[80:83], v[180:183], v[124:127]
	v_mfma_f32_16x16x32_bf16 v[108:111], v[56:59], v[208:211], v[108:111]
	v_mfma_f32_16x16x32_bf16 v[104:107], v[80:83], v[208:211], v[104:107]
	v_mfma_f32_16x16x32_bf16 v[88:91], v[56:59], v[216:219], v[88:91]
	v_mfma_f32_16x16x32_bf16 v[84:87], v[80:83], v[216:219], v[84:87]
	v_mfma_f32_16x16x32_bf16 v[148:151], v[60:63], v[176:179], v[148:151]
	v_mfma_f32_16x16x32_bf16 v[144:147], v[100:103], v[176:179], v[144:147]
	v_mfma_f32_16x16x32_bf16 v[128:131], v[60:63], v[204:207], v[128:131]
	v_mfma_f32_16x16x32_bf16 v[124:127], v[100:103], v[204:207], v[124:127]
	v_mfma_f32_16x16x32_bf16 v[108:111], v[60:63], v[212:215], v[108:111]
	v_mfma_f32_16x16x32_bf16 v[104:107], v[100:103], v[212:215], v[104:107]
	v_mfma_f32_16x16x32_bf16 v[88:91], v[60:63], v[220:223], v[88:91]
	v_mfma_f32_16x16x32_bf16 v[84:87], v[100:103], v[220:223], v[84:87]
	s_setprio 0
	s_setprio 1
	v_mfma_f32_16x16x32_bf16 v[136:139], v[120:123], v[172:175], v[136:139]
	v_mfma_f32_16x16x32_bf16 v[132:135], v[152:155], v[172:175], v[132:135]
	v_mfma_f32_16x16x32_bf16 v[116:119], v[120:123], v[180:183], v[116:119]
	v_mfma_f32_16x16x32_bf16 v[112:115], v[152:155], v[180:183], v[112:115]
	v_mfma_f32_16x16x32_bf16 v[96:99], v[120:123], v[208:211], v[96:99]
	v_mfma_f32_16x16x32_bf16 v[92:95], v[152:155], v[208:211], v[92:95]
	v_mfma_f32_16x16x32_bf16 v[76:79], v[120:123], v[216:219], v[76:79]
	v_mfma_f32_16x16x32_bf16 v[72:75], v[152:155], v[216:219], v[72:75]
	v_mfma_f32_16x16x32_bf16 v[136:139], v[140:143], v[176:179], v[136:139]
	v_mfma_f32_16x16x32_bf16 v[132:135], v[168:171], v[176:179], v[132:135]
	v_mfma_f32_16x16x32_bf16 v[116:119], v[140:143], v[204:207], v[116:119]
	v_mfma_f32_16x16x32_bf16 v[112:115], v[168:171], v[204:207], v[112:115]
	v_mfma_f32_16x16x32_bf16 v[96:99], v[140:143], v[212:215], v[96:99]
	v_mfma_f32_16x16x32_bf16 v[92:95], v[168:171], v[212:215], v[92:95]
	v_mfma_f32_16x16x32_bf16 v[76:79], v[140:143], v[220:223], v[76:79]
	v_mfma_f32_16x16x32_bf16 v[72:75], v[168:171], v[220:223], v[72:75]
	s_setprio 0
	s_barrier
	s_add_i32 s3, s3, s60
	v_lshl_add_u64 v[224:225], v[224:225], 0, s[72:73]
	s_mov_b32 m0, s3
	ds_read_b128 v[172:175], v202 offset:49152
	ds_read_b128 v[176:179], v202 offset:50176
	ds_read_b128 v[180:183], v202 offset:51200
	ds_read_b128 v[204:207], v202 offset:52224
	ds_read_b128 v[208:211], v202 offset:53248
	ds_read_b128 v[212:215], v202 offset:54272
	ds_read_b128 v[216:219], v202 offset:55296
	ds_read_b128 v[220:223], v202 offset:56320
	global_load_lds_dwordx4 v[224:225], off
	s_add_i32 m0, s3, 0x2000
	s_add_u32 s46, s94, 0x40080
	v_lshl_add_u64 v[224:225], v[226:227], 0, s[72:73]
	s_addc_u32 s47, s95, 0
	s_add_i32 s3, s33, s60
	global_load_lds_dwordx4 v[224:225], off
	v_lshl_add_u64 v[224:225], s[46:47], 0, v[158:159]
	s_mov_b32 m0, s3
	s_nop 0
	global_load_lds_dwordx4 v[224:225], off
	v_lshl_add_u64 v[224:225], s[46:47], 0, v[162:163]
	s_add_i32 m0, s3, 0x2000
	s_nop 0
	global_load_lds_dwordx4 v[224:225], off
	v_lshl_add_u64 v[224:225], v[234:235], 0, s[72:73]
	s_mov_b32 m0, s99
	s_nop 0
	global_load_lds_dwordx4 v[224:225], off
	v_lshl_add_u64 v[224:225], v[236:237], 0, s[72:73]
	s_mov_b32 m0, s16
	s_nop 0
	global_load_lds_dwordx4 v[224:225], off
	s_waitcnt vmcnt(8)
	s_waitcnt lgkmcnt(0)
	s_barrier
	s_setprio 1
	s_waitcnt lgkmcnt(0)
	v_mfma_f32_16x16x32_bf16 v[68:71], v[56:59], v[172:175], v[68:71]
	v_mfma_f32_16x16x32_bf16 v[64:67], v[80:83], v[172:175], v[64:67]
	v_mfma_f32_16x16x32_bf16 v[48:51], v[56:59], v[180:183], v[48:51]
	v_mfma_f32_16x16x32_bf16 v[44:47], v[80:83], v[180:183], v[44:47]
	v_mfma_f32_16x16x32_bf16 v[28:31], v[56:59], v[208:211], v[28:31]
	v_mfma_f32_16x16x32_bf16 v[24:27], v[80:83], v[208:211], v[24:27]
	v_mfma_f32_16x16x32_bf16 v[12:15], v[56:59], v[216:219], v[12:15]
	v_mfma_f32_16x16x32_bf16 v[8:11], v[80:83], v[216:219], v[8:11]
	v_mfma_f32_16x16x32_bf16 v[68:71], v[60:63], v[176:179], v[68:71]
	v_mfma_f32_16x16x32_bf16 v[64:67], v[100:103], v[176:179], v[64:67]
	v_mfma_f32_16x16x32_bf16 v[48:51], v[60:63], v[204:207], v[48:51]
	v_mfma_f32_16x16x32_bf16 v[44:47], v[100:103], v[204:207], v[44:47]
	v_mfma_f32_16x16x32_bf16 v[28:31], v[60:63], v[212:215], v[28:31]
	v_mfma_f32_16x16x32_bf16 v[24:27], v[100:103], v[212:215], v[24:27]
	v_mfma_f32_16x16x32_bf16 v[12:15], v[60:63], v[220:223], v[12:15]
	v_mfma_f32_16x16x32_bf16 v[8:11], v[100:103], v[220:223], v[8:11]
	s_setprio 0
	s_setprio 1
	v_mfma_f32_16x16x32_bf16 v[40:43], v[120:123], v[172:175], v[40:43]
	v_mfma_f32_16x16x32_bf16 v[56:59], v[140:143], v[176:179], v[40:43]
	v_mfma_f32_16x16x32_bf16 v[40:43], v[152:155], v[172:175], v[52:55]
	v_mfma_f32_16x16x32_bf16 v[36:39], v[120:123], v[180:183], v[36:39]
	v_mfma_f32_16x16x32_bf16 v[32:35], v[152:155], v[180:183], v[32:35]
	v_mfma_f32_16x16x32_bf16 v[20:23], v[120:123], v[208:211], v[20:23]
	v_mfma_f32_16x16x32_bf16 v[16:19], v[152:155], v[208:211], v[16:19]
	v_mfma_f32_16x16x32_bf16 v[4:7], v[120:123], v[216:219], v[4:7]
	v_mfma_f32_16x16x32_bf16 v[0:3], v[152:155], v[216:219], v[0:3]
	v_mfma_f32_16x16x32_bf16 v[52:55], v[168:171], v[176:179], v[40:43]
	v_mfma_f32_16x16x32_bf16 v[36:39], v[140:143], v[204:207], v[36:39]
	v_mfma_f32_16x16x32_bf16 v[32:35], v[168:171], v[204:207], v[32:35]
	v_mfma_f32_16x16x32_bf16 v[20:23], v[140:143], v[212:215], v[20:23]
	v_mfma_f32_16x16x32_bf16 v[16:19], v[168:171], v[212:215], v[16:19]
	v_mfma_f32_16x16x32_bf16 v[4:7], v[140:143], v[220:223], v[4:7]
	v_mfma_f32_16x16x32_bf16 v[0:3], v[168:171], v[220:223], v[0:3]
	s_setprio 0
	s_barrier
	s_add_i32 s31, s31, 2
	s_cmp_gt_u32 s31, 13
	s_mov_b64 s[46:47], s[50:51]
	s_cbranch_scc1 .Lpeel_exit_mixin
.LBB0_329:
	s_add_u32 s50, s46, 0x100
	s_addc_u32 s51, s47, 0
	s_add_u32 s3, s46, 0xfffff900
	v_cmp_gt_u64_e32 vcc, s[50:51], v[192:193]
	s_addc_u32 s33, s47, -1
	s_and_b64 s[76:77], vcc, exec
	s_cselect_b32 s50, s3, s50
	s_cselect_b32 s51, s33, s51
	s_add_u32 s3, s92, s50
	s_addc_u32 s33, s93, s51
	s_add_u32 s43, s36, s50
	s_addc_u32 s54, s37, s51
	s_add_i32 s69, 0, 0x10000
	s_cmp_eq_u32 s31, 12
	s_cselect_b32 s97, s7, s33
	s_cselect_b32 s96, s11, s3
	s_cselect_b32 s95, s0, s54
	s_cselect_b32 s94, s29, s43
	s_add_i32 s3, 0, 0x14000
	v_add_u32_e32 v100, s69, v184
	v_add_u32_e32 v168, s3, v184
	ds_read_b128 v[40:43], v100
	ds_read_b128 v[60:63], v100 offset:1024
	ds_read_b128 v[80:83], v100 offset:2048
	ds_read_b128 v[100:103], v100 offset:3072
	ds_read_b128 v[120:123], v168
	ds_read_b128 v[140:143], v168 offset:1024
	ds_read_b128 v[152:155], v168 offset:2048
	ds_read_b128 v[168:171], v168 offset:3072
	s_add_u32 s33, s92, s46
	s_addc_u32 s43, s93, s47
	s_add_u32 s46, s33, 0x40080
	s_addc_u32 s47, s43, 0
	v_lshl_add_u64 v[224:225], s[46:47], 0, v[156:157]
	s_add_i32 m0, s23, 0xc000
	ds_read_b128 v[172:175], v202
	ds_read_b128 v[176:179], v202 offset:1024
	ds_read_b128 v[180:183], v202 offset:2048
	ds_read_b128 v[204:207], v202 offset:3072
	ds_read_b128 v[208:211], v202 offset:4096
	ds_read_b128 v[212:215], v202 offset:5120
	ds_read_b128 v[216:219], v202 offset:6144
	ds_read_b128 v[220:223], v202 offset:7168
	global_load_lds_dwordx4 v[224:225], off
	v_lshl_add_u64 v[224:225], s[46:47], 0, v[160:161]
	s_add_i32 m0, s23, 0xe000
	s_nop 0
	global_load_lds_dwordx4 v[224:225], off
	s_waitcnt vmcnt(8)
	s_waitcnt lgkmcnt(0)
	s_barrier
	s_setprio 1
	s_waitcnt lgkmcnt(0)
	v_mfma_f32_16x16x32_bf16 v[148:151], v[40:43], v[172:175], v[148:151]
	v_mfma_f32_16x16x32_bf16 v[144:147], v[80:83], v[172:175], v[144:147]
	v_mfma_f32_16x16x32_bf16 v[128:131], v[40:43], v[180:183], v[128:131]
	v_mfma_f32_16x16x32_bf16 v[124:127], v[80:83], v[180:183], v[124:127]
	v_mfma_f32_16x16x32_bf16 v[108:111], v[40:43], v[208:211], v[108:111]
	v_mfma_f32_16x16x32_bf16 v[104:107], v[80:83], v[208:211], v[104:107]
	v_mfma_f32_16x16x32_bf16 v[88:91], v[40:43], v[216:219], v[88:91]
	v_mfma_f32_16x16x32_bf16 v[84:87], v[80:83], v[216:219], v[84:87]
	v_mfma_f32_16x16x32_bf16 v[148:151], v[60:63], v[176:179], v[148:151]
	v_mfma_f32_16x16x32_bf16 v[144:147], v[100:103], v[176:179], v[144:147]
	v_mfma_f32_16x16x32_bf16 v[128:131], v[60:63], v[204:207], v[128:131]
	v_mfma_f32_16x16x32_bf16 v[124:127], v[100:103], v[204:207], v[124:127]
	v_mfma_f32_16x16x32_bf16 v[108:111], v[60:63], v[212:215], v[108:111]
	v_mfma_f32_16x16x32_bf16 v[104:107], v[100:103], v[212:215], v[104:107]
	v_mfma_f32_16x16x32_bf16 v[88:91], v[60:63], v[220:223], v[88:91]
	v_mfma_f32_16x16x32_bf16 v[84:87], v[100:103], v[220:223], v[84:87]
	s_setprio 0
	s_setprio 1
	v_mfma_f32_16x16x32_bf16 v[136:139], v[120:123], v[172:175], v[136:139]
	v_mfma_f32_16x16x32_bf16 v[132:135], v[152:155], v[172:175], v[132:135]
	v_mfma_f32_16x16x32_bf16 v[116:119], v[120:123], v[180:183], v[116:119]
	v_mfma_f32_16x16x32_bf16 v[112:115], v[152:155], v[180:183], v[112:115]
	v_mfma_f32_16x16x32_bf16 v[96:99], v[120:123], v[208:211], v[96:99]
	v_mfma_f32_16x16x32_bf16 v[92:95], v[152:155], v[208:211], v[92:95]
	v_mfma_f32_16x16x32_bf16 v[76:79], v[120:123], v[216:219], v[76:79]
	v_mfma_f32_16x16x32_bf16 v[72:75], v[152:155], v[216:219], v[72:75]
	v_mfma_f32_16x16x32_bf16 v[136:139], v[140:143], v[176:179], v[136:139]
	v_mfma_f32_16x16x32_bf16 v[132:135], v[168:171], v[176:179], v[132:135]
	v_mfma_f32_16x16x32_bf16 v[116:119], v[140:143], v[204:207], v[116:119]
	v_mfma_f32_16x16x32_bf16 v[112:115], v[168:171], v[204:207], v[112:115]
	v_mfma_f32_16x16x32_bf16 v[96:99], v[140:143], v[212:215], v[96:99]
	v_mfma_f32_16x16x32_bf16 v[92:95], v[168:171], v[212:215], v[92:95]
	v_mfma_f32_16x16x32_bf16 v[76:79], v[140:143], v[220:223], v[76:79]
	v_mfma_f32_16x16x32_bf16 v[72:75], v[168:171], v[220:223], v[72:75]
	s_setprio 0
	s_barrier
	s_add_i32 s33, s69, s60
	v_lshl_add_u64 v[224:225], s[94:95], 0, v[158:159]
	s_mov_b32 m0, s33
	ds_read_b128 v[172:175], v202 offset:16384
	ds_read_b128 v[176:179], v202 offset:17408
	ds_read_b128 v[180:183], v202 offset:18432
	ds_read_b128 v[204:207], v202 offset:19456
	ds_read_b128 v[208:211], v202 offset:20480
	ds_read_b128 v[212:215], v202 offset:21504
	ds_read_b128 v[216:219], v202 offset:22528
	ds_read_b128 v[220:223], v202 offset:23552
	global_load_lds_dwordx4 v[224:225], off
	s_add_i32 m0, s33, 0x2000
	s_add_u32 s46, s94, 0x40000
	v_lshl_add_u64 v[226:227], s[94:95], 0, v[162:163]
	s_addc_u32 s47, s95, 0
	s_add_i32 s3, s3, s60
	global_load_lds_dwordx4 v[226:227], off
	v_lshl_add_u64 v[234:235], s[46:47], 0, v[158:159]
	s_mov_b32 m0, s3
	v_lshl_add_u64 v[236:237], s[96:97], 0, v[160:161]
	global_load_lds_dwordx4 v[234:235], off
	v_lshl_add_u64 v[234:235], s[46:47], 0, v[162:163]
	s_add_i32 m0, s3, 0x2000
	s_nop 0
	global_load_lds_dwordx4 v[234:235], off
	v_lshl_add_u64 v[234:235], s[96:97], 0, v[156:157]
	s_mov_b32 m0, s23
	s_nop 0
	global_load_lds_dwordx4 v[234:235], off
	s_mov_b32 m0, s87
	s_nop 0
	global_load_lds_dwordx4 v[236:237], off
	s_waitcnt vmcnt(8)
	s_waitcnt lgkmcnt(0)
	s_barrier
	s_setprio 1
	s_waitcnt lgkmcnt(0)
	v_mfma_f32_16x16x32_bf16 v[68:71], v[40:43], v[172:175], v[68:71]
	v_mfma_f32_16x16x32_bf16 v[64:67], v[80:83], v[172:175], v[64:67]
	v_mfma_f32_16x16x32_bf16 v[48:51], v[40:43], v[180:183], v[48:51]
	v_mfma_f32_16x16x32_bf16 v[44:47], v[80:83], v[180:183], v[44:47]
	v_mfma_f32_16x16x32_bf16 v[28:31], v[40:43], v[208:211], v[28:31]
	v_mfma_f32_16x16x32_bf16 v[24:27], v[80:83], v[208:211], v[24:27]
	v_mfma_f32_16x16x32_bf16 v[12:15], v[40:43], v[216:219], v[12:15]
	v_mfma_f32_16x16x32_bf16 v[8:11], v[80:83], v[216:219], v[8:11]
	v_mfma_f32_16x16x32_bf16 v[68:71], v[60:63], v[176:179], v[68:71]
	v_mfma_f32_16x16x32_bf16 v[64:67], v[100:103], v[176:179], v[64:67]
	v_mfma_f32_16x16x32_bf16 v[48:51], v[60:63], v[204:207], v[48:51]
	v_mfma_f32_16x16x32_bf16 v[44:47], v[100:103], v[204:207], v[44:47]
	v_mfma_f32_16x16x32_bf16 v[28:31], v[60:63], v[212:215], v[28:31]
	v_mfma_f32_16x16x32_bf16 v[24:27], v[100:103], v[212:215], v[24:27]
	v_mfma_f32_16x16x32_bf16 v[12:15], v[60:63], v[220:223], v[12:15]
	v_mfma_f32_16x16x32_bf16 v[8:11], v[100:103], v[220:223], v[8:11]
	s_setprio 0
	s_setprio 1
	v_mfma_f32_16x16x32_bf16 v[52:55], v[152:155], v[172:175], v[52:55]
	v_mfma_f32_16x16x32_bf16 v[36:39], v[120:123], v[180:183], v[36:39]
	v_mfma_f32_16x16x32_bf16 v[32:35], v[152:155], v[180:183], v[32:35]
	v_mfma_f32_16x16x32_bf16 v[20:23], v[120:123], v[208:211], v[20:23]
	v_mfma_f32_16x16x32_bf16 v[16:19], v[152:155], v[208:211], v[16:19]
	v_mfma_f32_16x16x32_bf16 v[4:7], v[120:123], v[216:219], v[4:7]
	v_mfma_f32_16x16x32_bf16 v[0:3], v[152:155], v[216:219], v[0:3]
	v_mfma_f32_16x16x32_bf16 v[40:43], v[120:123], v[172:175], v[56:59]
	v_mfma_f32_16x16x32_bf16 v[52:55], v[168:171], v[176:179], v[52:55]
	v_mfma_f32_16x16x32_bf16 v[36:39], v[140:143], v[204:207], v[36:39]
	v_mfma_f32_16x16x32_bf16 v[32:35], v[168:171], v[204:207], v[32:35]
	v_mfma_f32_16x16x32_bf16 v[20:23], v[140:143], v[212:215], v[20:23]
	v_mfma_f32_16x16x32_bf16 v[16:19], v[168:171], v[212:215], v[16:19]
	v_mfma_f32_16x16x32_bf16 v[4:7], v[140:143], v[220:223], v[4:7]
	v_mfma_f32_16x16x32_bf16 v[0:3], v[168:171], v[220:223], v[0:3]
	v_mfma_f32_16x16x32_bf16 v[40:43], v[140:143], v[176:179], v[40:43]
	s_setprio 0
	s_barrier
	s_add_i32 s3, 0, 0x18000
	s_add_i32 s33, 0, 0x1c000
	v_add_u32_e32 v100, s3, v184
	v_add_u32_e32 v168, s33, v184
	ds_read_b128 v[56:59], v100
	ds_read_b128 v[60:63], v100 offset:1024
	ds_read_b128 v[80:83], v100 offset:2048
	ds_read_b128 v[100:103], v100 offset:3072
	ds_read_b128 v[120:123], v168
	ds_read_b128 v[140:143], v168 offset:1024
	ds_read_b128 v[152:155], v168 offset:2048
	ds_read_b128 v[168:171], v168 offset:3072
	s_add_u32 s46, s96, 0x40000
	s_addc_u32 s47, s97, 0
	s_mov_b32 m0, s89
	v_lshl_add_u64 v[238:239], s[46:47], 0, v[156:157]
	ds_read_b128 v[172:175], v202 offset:32768
	ds_read_b128 v[176:179], v202 offset:33792
	ds_read_b128 v[180:183], v202 offset:34816
	ds_read_b128 v[204:207], v202 offset:35840
	ds_read_b128 v[208:211], v202 offset:36864
	ds_read_b128 v[212:215], v202 offset:37888
	ds_read_b128 v[216:219], v202 offset:38912
	ds_read_b128 v[220:223], v202 offset:39936
	global_load_lds_dwordx4 v[238:239], off
	v_lshl_add_u64 v[238:239], s[46:47], 0, v[160:161]
	s_mov_b32 m0, s98
	s_nop 0
	global_load_lds_dwordx4 v[238:239], off
	s_waitcnt vmcnt(8)
	s_waitcnt lgkmcnt(0)
	s_barrier
	s_setprio 1
	s_waitcnt lgkmcnt(0)
	v_mfma_f32_16x16x32_bf16 v[148:151], v[56:59], v[172:175], v[148:151]
	v_mfma_f32_16x16x32_bf16 v[144:147], v[80:83], v[172:175], v[144:147]
	v_mfma_f32_16x16x32_bf16 v[128:131], v[56:59], v[180:183], v[128:131]
	v_mfma_f32_16x16x32_bf16 v[124:127], v[80:83], v[180:183], v[124:127]
	v_mfma_f32_16x16x32_bf16 v[108:111], v[56:59], v[208:211], v[108:111]
	v_mfma_f32_16x16x32_bf16 v[104:107], v[80:83], v[208:211], v[104:107]
	v_mfma_f32_16x16x32_bf16 v[88:91], v[56:59], v[216:219], v[88:91]
	v_mfma_f32_16x16x32_bf16 v[84:87], v[80:83], v[216:219], v[84:87]
	v_mfma_f32_16x16x32_bf16 v[148:151], v[60:63], v[176:179], v[148:151]
	v_mfma_f32_16x16x32_bf16 v[144:147], v[100:103], v[176:179], v[144:147]
	v_mfma_f32_16x16x32_bf16 v[128:131], v[60:63], v[204:207], v[128:131]
	v_mfma_f32_16x16x32_bf16 v[124:127], v[100:103], v[204:207], v[124:127]
	v_mfma_f32_16x16x32_bf16 v[108:111], v[60:63], v[212:215], v[108:111]
	v_mfma_f32_16x16x32_bf16 v[104:107], v[100:103], v[212:215], v[104:107]
	v_mfma_f32_16x16x32_bf16 v[88:91], v[60:63], v[220:223], v[88:91]
	v_mfma_f32_16x16x32_bf16 v[84:87], v[100:103], v[220:223], v[84:87]
	s_setprio 0
	s_setprio 1
	v_mfma_f32_16x16x32_bf16 v[136:139], v[120:123], v[172:175], v[136:139]
	v_mfma_f32_16x16x32_bf16 v[132:135], v[152:155], v[172:175], v[132:135]
	v_mfma_f32_16x16x32_bf16 v[116:119], v[120:123], v[180:183], v[116:119]
	v_mfma_f32_16x16x32_bf16 v[112:115], v[152:155], v[180:183], v[112:115]
	v_mfma_f32_16x16x32_bf16 v[96:99], v[120:123], v[208:211], v[96:99]
	v_mfma_f32_16x16x32_bf16 v[92:95], v[152:155], v[208:211], v[92:95]
	v_mfma_f32_16x16x32_bf16 v[76:79], v[120:123], v[216:219], v[76:79]
	v_mfma_f32_16x16x32_bf16 v[72:75], v[152:155], v[216:219], v[72:75]
	v_mfma_f32_16x16x32_bf16 v[136:139], v[140:143], v[176:179], v[136:139]
	v_mfma_f32_16x16x32_bf16 v[132:135], v[168:171], v[176:179], v[132:135]
	v_mfma_f32_16x16x32_bf16 v[116:119], v[140:143], v[204:207], v[116:119]
	v_mfma_f32_16x16x32_bf16 v[112:115], v[168:171], v[204:207], v[112:115]
	v_mfma_f32_16x16x32_bf16 v[96:99], v[140:143], v[212:215], v[96:99]
	v_mfma_f32_16x16x32_bf16 v[92:95], v[168:171], v[212:215], v[92:95]
	v_mfma_f32_16x16x32_bf16 v[76:79], v[140:143], v[220:223], v[76:79]
	v_mfma_f32_16x16x32_bf16 v[72:75], v[168:171], v[220:223], v[72:75]
	s_setprio 0
	s_barrier
	s_add_i32 s3, s3, s60
	v_lshl_add_u64 v[224:225], v[224:225], 0, s[72:73]
	s_mov_b32 m0, s3
	ds_read_b128 v[172:175], v202 offset:49152
	ds_read_b128 v[176:179], v202 offset:50176
	ds_read_b128 v[180:183], v202 offset:51200
	ds_read_b128 v[204:207], v202 offset:52224
	ds_read_b128 v[208:211], v202 offset:53248
	ds_read_b128 v[212:215], v202 offset:54272
	ds_read_b128 v[216:219], v202 offset:55296
	ds_read_b128 v[220:223], v202 offset:56320
	global_load_lds_dwordx4 v[224:225], off
	s_add_i32 m0, s3, 0x2000
	s_add_u32 s46, s94, 0x40080
	v_lshl_add_u64 v[224:225], v[226:227], 0, s[72:73]
	s_addc_u32 s47, s95, 0
	s_add_i32 s3, s33, s60
	global_load_lds_dwordx4 v[224:225], off
	v_lshl_add_u64 v[224:225], s[46:47], 0, v[158:159]
	s_mov_b32 m0, s3
	s_nop 0
	global_load_lds_dwordx4 v[224:225], off
	v_lshl_add_u64 v[224:225], s[46:47], 0, v[162:163]
	s_add_i32 m0, s3, 0x2000
	s_nop 0
	global_load_lds_dwordx4 v[224:225], off
	v_lshl_add_u64 v[224:225], v[234:235], 0, s[72:73]
	s_mov_b32 m0, s99
	s_nop 0
	global_load_lds_dwordx4 v[224:225], off
	v_lshl_add_u64 v[224:225], v[236:237], 0, s[72:73]
	s_mov_b32 m0, s16
	s_nop 0
	global_load_lds_dwordx4 v[224:225], off
	s_waitcnt vmcnt(8)
	s_waitcnt lgkmcnt(0)
	s_barrier
	s_setprio 1
	s_waitcnt lgkmcnt(0)
	v_mfma_f32_16x16x32_bf16 v[68:71], v[56:59], v[172:175], v[68:71]
	v_mfma_f32_16x16x32_bf16 v[64:67], v[80:83], v[172:175], v[64:67]
	v_mfma_f32_16x16x32_bf16 v[48:51], v[56:59], v[180:183], v[48:51]
	v_mfma_f32_16x16x32_bf16 v[44:47], v[80:83], v[180:183], v[44:47]
	v_mfma_f32_16x16x32_bf16 v[28:31], v[56:59], v[208:211], v[28:31]
	v_mfma_f32_16x16x32_bf16 v[24:27], v[80:83], v[208:211], v[24:27]
	v_mfma_f32_16x16x32_bf16 v[12:15], v[56:59], v[216:219], v[12:15]
	v_mfma_f32_16x16x32_bf16 v[8:11], v[80:83], v[216:219], v[8:11]
	v_mfma_f32_16x16x32_bf16 v[68:71], v[60:63], v[176:179], v[68:71]
	v_mfma_f32_16x16x32_bf16 v[64:67], v[100:103], v[176:179], v[64:67]
	v_mfma_f32_16x16x32_bf16 v[48:51], v[60:63], v[204:207], v[48:51]
	v_mfma_f32_16x16x32_bf16 v[44:47], v[100:103], v[204:207], v[44:47]
	v_mfma_f32_16x16x32_bf16 v[28:31], v[60:63], v[212:215], v[28:31]
	v_mfma_f32_16x16x32_bf16 v[24:27], v[100:103], v[212:215], v[24:27]
	v_mfma_f32_16x16x32_bf16 v[12:15], v[60:63], v[220:223], v[12:15]
	v_mfma_f32_16x16x32_bf16 v[8:11], v[100:103], v[220:223], v[8:11]
	s_setprio 0
	s_setprio 1
	v_mfma_f32_16x16x32_bf16 v[40:43], v[120:123], v[172:175], v[40:43]
	v_mfma_f32_16x16x32_bf16 v[56:59], v[140:143], v[176:179], v[40:43]
	v_mfma_f32_16x16x32_bf16 v[40:43], v[152:155], v[172:175], v[52:55]
	v_mfma_f32_16x16x32_bf16 v[36:39], v[120:123], v[180:183], v[36:39]
	v_mfma_f32_16x16x32_bf16 v[32:35], v[152:155], v[180:183], v[32:35]
	v_mfma_f32_16x16x32_bf16 v[20:23], v[120:123], v[208:211], v[20:23]
	v_mfma_f32_16x16x32_bf16 v[16:19], v[152:155], v[208:211], v[16:19]
	v_mfma_f32_16x16x32_bf16 v[4:7], v[120:123], v[216:219], v[4:7]
	v_mfma_f32_16x16x32_bf16 v[0:3], v[152:155], v[216:219], v[0:3]
	v_mfma_f32_16x16x32_bf16 v[52:55], v[168:171], v[176:179], v[40:43]
	v_mfma_f32_16x16x32_bf16 v[36:39], v[140:143], v[204:207], v[36:39]
	v_mfma_f32_16x16x32_bf16 v[32:35], v[168:171], v[204:207], v[32:35]
	v_mfma_f32_16x16x32_bf16 v[20:23], v[140:143], v[212:215], v[20:23]
	v_mfma_f32_16x16x32_bf16 v[16:19], v[168:171], v[212:215], v[16:19]
	v_mfma_f32_16x16x32_bf16 v[4:7], v[140:143], v[220:223], v[4:7]
	v_mfma_f32_16x16x32_bf16 v[0:3], v[168:171], v[220:223], v[0:3]
	s_setprio 0
	s_barrier
	s_add_i32 s31, s31, 2
	s_cmp_gt_u32 s31, 13
	s_mov_b64 s[46:47], s[50:51]
	s_cbranch_scc0 .LBB0_329
.Lpeel_exit_mixin:
	s_and_b64 vcc, exec, s[26:27]
	s_cbranch_vccz .LBB0_332
	s_barrier
.LBB0_332:
	v_lshl_add_u32 v168, s1, 12, v186
	ds_read_b128 v[40:43], v168
	ds_read_b128 v[152:155], v168 offset:256
	v_lshl_or_b32 v188, s22, 8, v187
	s_waitcnt lgkmcnt(0)
	v_mov_b32_e32 v60, v41
	v_mov_b32_e32 v61, v42
	v_mov_b32_e32 v41, v43
	v_pk_add_f32 v[40:41], v[60:61], v[40:41]
	s_nop 0
	v_add_f32_e32 v40, v40, v41
	v_fmamk_f32 v169, v40, 0x3a800000, v229
	ds_read_b128 v[140:143], v168 offset:512
	ds_read_b128 v[120:123], v168 offset:768
	ds_read_b128 v[100:103], v168 offset:2048
	ds_read_b128 v[80:83], v168 offset:2304
	ds_read_b128 v[60:63], v168 offset:2560
	ds_read_b128 v[40:43], v168 offset:2816
	v_rsq_f32_e32 v172, v169
	v_lshl_add_u32 v168, s6, 8, v165
	v_ashrrev_i32_e32 v169, 31, v168
	s_cmp_gt_i32 s22, 1
	v_lshlrev_b64 v[170:171], 10, v[168:169]
	v_pk_mul_f32 v[148:149], v[148:149], v[172:173] op_sel_hi:[1,0]
	v_pk_mul_f32 v[150:151], v[150:151], v[172:173] op_sel_hi:[1,0]
	v_pk_mul_f32 v[144:145], v[144:145], v[172:173] op_sel_hi:[1,0]
	v_pk_mul_f32 v[146:147], v[146:147], v[172:173] op_sel_hi:[1,0]
	s_cselect_b64 s[36:37], -1, 0
	s_cmp_lt_i32 s22, 2
	s_mov_b64 s[6:7], -1
	s_mov_b64 s[50:51], 0x100
	s_cbranch_scc1 .LBB0_338
	v_pk_mul_f32 v[176:177], v[150:151], v[150:151]
	v_pk_mul_f32 v[174:175], v[148:149], v[148:149]
	v_pk_fma_f32 v[176:177], v[176:177], s[64:65], 1.0 op_sel_hi:[1,0,0]
	v_pk_mul_f32 v[180:181], v[146:147], v[146:147]
	v_pk_mul_f32 v[176:177], v[150:151], v[176:177]
	v_pk_fma_f32 v[174:175], v[174:175], s[64:65], 1.0 op_sel_hi:[1,0,0]
	v_pk_mul_f32 v[176:177], v[176:177], s[66:67] op_sel_hi:[1,0]
	v_pk_fma_f32 v[180:181], v[180:181], s[64:65], 1.0 op_sel_hi:[1,0,0]
	v_pk_mul_f32 v[176:177], v[176:177], s[68:69] op_sel_hi:[1,0]
	v_pk_mul_f32 v[174:175], v[148:149], v[174:175]
	v_exp_f32_e32 v176, v176
	v_exp_f32_e32 v177, v177
	v_pk_mul_f32 v[180:181], v[146:147], v[180:181]
	v_pk_mul_f32 v[174:175], v[174:175], s[66:67] op_sel_hi:[1,0]
	v_pk_mul_f32 v[180:181], v[180:181], s[66:67] op_sel_hi:[1,0]
	v_pk_add_f32 v[176:177], v[176:177], 1.0 op_sel_hi:[1,0]
	v_pk_mul_f32 v[174:175], v[174:175], s[68:69] op_sel_hi:[1,0]
	v_rcp_f32_e32 v178, v176
	v_rcp_f32_e32 v179, v177
	v_pk_mul_f32 v[176:177], v[144:145], v[144:145]
	v_pk_mul_f32 v[180:181], v[180:181], s[68:69] op_sel_hi:[1,0]
	v_pk_fma_f32 v[176:177], v[176:177], s[64:65], 1.0 op_sel_hi:[1,0,0]
	v_exp_f32_e32 v174, v174
	v_pk_mul_f32 v[176:177], v[144:145], v[176:177]
	v_exp_f32_e32 v175, v175
	v_pk_mul_f32 v[176:177], v[176:177], s[66:67] op_sel_hi:[1,0]
	v_exp_f32_e32 v180, v180
	v_pk_mul_f32 v[176:177], v[176:177], s[68:69] op_sel_hi:[1,0]
	v_exp_f32_e32 v181, v181
	v_exp_f32_e32 v176, v176
	v_exp_f32_e32 v177, v177
	v_pk_add_f32 v[174:175], v[174:175], 1.0 op_sel_hi:[1,0]
	v_pk_mul_f32 v[178:179], v[150:151], v[178:179]
	v_rcp_f32_e32 v174, v174
	v_pk_add_f32 v[176:177], v[176:177], 1.0 op_sel_hi:[1,0]
	v_rcp_f32_e32 v175, v175
	v_rcp_f32_e32 v182, v176
	v_rcp_f32_e32 v183, v177
	v_pk_add_f32 v[176:177], v[180:181], 1.0 op_sel_hi:[1,0]
	s_cmp_gt_u32 s22, 3
	v_rcp_f32_e32 v204, v176
	v_rcp_f32_e32 v205, v177
	v_pk_mul_f32 v[176:177], v[148:149], v[174:175]
	v_pk_mul_f32 v[180:181], v[144:145], v[182:183]
	v_pk_mul_f32 v[174:175], v[146:147], v[204:205]
	s_cbranch_scc0 .LBB0_335
	v_lshl_add_u64 v[182:183], s[20:21], 0, v[170:171]
	s_movk_i32 s0, 0xf800
	v_lshl_add_u64 v[182:183], v[188:189], 1, v[182:183]
	s_mov_b32 s1, -1
	v_lshl_add_u64 v[182:183], v[182:183], 0, s[0:1]
	s_mov_b64 s[6:7], 0

.LBB0_489:
	s_add_u32 s0, s34, s92
	s_addc_u32 s43, s35, 0
	s_mov_b64 s[36:37], 0
	s_mov_b32 s86, 0
	s_add_u32 s38, s36, 0x100
	s_addc_u32 s39, s37, 0
	v_mov_b64_e32 v[120:121], s[24:25]
	v_cmp_ge_u64_e32 vcc, s[38:39], v[120:121]
	s_and_b64 s[46:47], vcc, exec
	s_cselect_b32 s47, s24, 0
	s_cselect_b32 s46, 0, 0
	s_sub_u32 s38, s38, s47
	s_subb_u32 s39, s39, s46
	s_sub_u32 s47, s36, s47
	s_subb_u32 s46, s37, s46
	s_add_u32 vcc_lo, s34, s47
	s_addc_u32 vcc_hi, s35, s46
	s_add_u32 vcc_lo, vcc_lo, 0x100
	s_addc_u32 vcc_hi, vcc_hi, 0
	s_add_u32 s47, s30, s47
	s_addc_u32 s46, s31, s46
	s_add_u32 s69, s47, 0x100
	s_addc_u32 s3, s46, 0
	s_add_i32 s33, 0, 0x10000
	s_cmp_eq_u32 s99, s86
	s_cselect_b32 s47, s11, vcc_hi
	s_cselect_b32 s46, s10, vcc_lo
	s_cselect_b32 vcc_hi, s29, s3
	s_cselect_b32 vcc_lo, s28, s69
	s_add_i32 s3, 0, 0x14000
	v_add_u32_e32 v132, s33, v234
	v_add_u32_e32 v148, s3, v234
	ds_read_b128 v[120:123], v132
	ds_read_b128 v[124:127], v132 offset:1024
	ds_read_b128 v[128:131], v132 offset:2048
	ds_read_b128 v[132:135], v132 offset:3072
	ds_read_b128 v[136:139], v148
	ds_read_b128 v[140:143], v148 offset:1024
	ds_read_b128 v[144:147], v148 offset:2048
	ds_read_b128 v[148:151], v148 offset:3072
	s_add_u32 s36, s0, s36
	s_addc_u32 s37, s43, s37
	v_lshl_add_u64 v[212:213], s[36:37], 0, v[202:203]
	v_lshl_add_u64 v[212:213], v[212:213], 0, s[72:73]
	s_add_i32 m0, s94, 0xc000
	ds_read_b128 v[152:155], v248
	ds_read_b128 v[156:159], v248 offset:1024
	ds_read_b128 v[160:163], v248 offset:2048
	ds_read_b128 v[172:175], v248 offset:3072
	ds_read_b128 v[176:179], v248 offset:4096
	ds_read_b128 v[180:183], v248 offset:5120
	ds_read_b128 v[184:187], v248 offset:6144
	ds_read_b128 v[208:211], v248 offset:7168
	global_load_lds_dwordx4 v[212:213], off
	v_lshl_add_u64 v[212:213], s[36:37], 0, v[204:205]
	v_lshl_add_u64 v[212:213], v[212:213], 0, s[72:73]
	s_add_i32 m0, s94, 0xe000
	s_nop 0
	global_load_lds_dwordx4 v[212:213], off
	s_waitcnt vmcnt(8)
	s_waitcnt lgkmcnt(0)
	s_barrier
	s_setprio 1
	s_waitcnt lgkmcnt(0)
	v_mfma_f32_16x16x32_bf16 v[168:171], v[120:123], v[152:155], 0
	v_mfma_f32_16x16x32_bf16 v[164:167], v[128:131], v[152:155], 0
	v_mfma_f32_16x16x32_bf16 v[108:111], v[120:123], v[160:163], 0
	v_mfma_f32_16x16x32_bf16 v[104:107], v[128:131], v[160:163], 0
	v_mfma_f32_16x16x32_bf16 v[92:95], v[120:123], v[176:179], 0
	v_mfma_f32_16x16x32_bf16 v[88:91], v[128:131], v[176:179], 0
	v_mfma_f32_16x16x32_bf16 v[76:79], v[120:123], v[184:187], 0
	v_mfma_f32_16x16x32_bf16 v[72:75], v[128:131], v[184:187], 0
	v_mfma_f32_16x16x32_bf16 v[168:171], v[124:127], v[156:159], v[168:171]
	v_mfma_f32_16x16x32_bf16 v[164:167], v[132:135], v[156:159], v[164:167]
	v_mfma_f32_16x16x32_bf16 v[108:111], v[124:127], v[172:175], v[108:111]
	v_mfma_f32_16x16x32_bf16 v[104:107], v[132:135], v[172:175], v[104:107]
	v_mfma_f32_16x16x32_bf16 v[92:95], v[124:127], v[180:183], v[92:95]
	v_mfma_f32_16x16x32_bf16 v[88:91], v[132:135], v[180:183], v[88:91]
	v_mfma_f32_16x16x32_bf16 v[76:79], v[124:127], v[208:211], v[76:79]
	v_mfma_f32_16x16x32_bf16 v[72:75], v[132:135], v[208:211], v[72:75]
	s_setprio 0
	s_setprio 1
	v_mfma_f32_16x16x32_bf16 v[116:119], v[136:139], v[152:155], 0
	v_mfma_f32_16x16x32_bf16 v[112:115], v[144:147], v[152:155], 0
	v_mfma_f32_16x16x32_bf16 v[100:103], v[136:139], v[160:163], 0
	v_mfma_f32_16x16x32_bf16 v[96:99], v[144:147], v[160:163], 0
	v_mfma_f32_16x16x32_bf16 v[84:87], v[136:139], v[176:179], 0
	v_mfma_f32_16x16x32_bf16 v[80:83], v[144:147], v[176:179], 0
	v_mfma_f32_16x16x32_bf16 v[68:71], v[136:139], v[184:187], 0
	v_mfma_f32_16x16x32_bf16 v[64:67], v[144:147], v[184:187], 0
	v_mfma_f32_16x16x32_bf16 v[116:119], v[140:143], v[156:159], v[116:119]
	v_mfma_f32_16x16x32_bf16 v[112:115], v[148:151], v[156:159], v[112:115]
	v_mfma_f32_16x16x32_bf16 v[100:103], v[140:143], v[172:175], v[100:103]
	v_mfma_f32_16x16x32_bf16 v[96:99], v[148:151], v[172:175], v[96:99]
	v_mfma_f32_16x16x32_bf16 v[84:87], v[140:143], v[180:183], v[84:87]
	v_mfma_f32_16x16x32_bf16 v[80:83], v[148:151], v[180:183], v[80:83]
	v_mfma_f32_16x16x32_bf16 v[68:71], v[140:143], v[208:211], v[68:71]
	v_mfma_f32_16x16x32_bf16 v[64:67], v[148:151], v[208:211], v[64:67]
	s_setprio 0
	s_barrier
	s_add_i32 s33, s33, s89
	v_lshl_add_u64 v[212:213], vcc, 0, v[188:189]
	s_mov_b32 m0, s33
	ds_read_b128 v[152:155], v248 offset:16384
	ds_read_b128 v[156:159], v248 offset:17408
	ds_read_b128 v[160:163], v248 offset:18432
	ds_read_b128 v[172:175], v248 offset:19456
	ds_read_b128 v[176:179], v248 offset:20480
	ds_read_b128 v[180:183], v248 offset:21504
	ds_read_b128 v[184:187], v248 offset:22528
	ds_read_b128 v[208:211], v248 offset:23552
	global_load_lds_dwordx4 v[212:213], off
	s_add_i32 m0, s33, 0x2000
	s_add_u32 s36, vcc_lo, s92
	v_lshl_add_u64 v[214:215], vcc, 0, v[206:207]
	s_addc_u32 s37, vcc_hi, 0
	s_add_i32 s3, s3, s89
	global_load_lds_dwordx4 v[214:215], off
	v_lshl_add_u64 v[216:217], s[36:37], 0, v[188:189]
	s_mov_b32 m0, s3
	v_lshl_add_u64 v[218:219], s[36:37], 0, v[206:207]
	global_load_lds_dwordx4 v[216:217], off
	s_add_i32 m0, s3, 0x2000
	v_lshl_add_u64 v[220:221], s[46:47], 0, v[202:203]
	global_load_lds_dwordx4 v[218:219], off
	s_mov_b32 m0, s94
	v_lshl_add_u64 v[222:223], s[46:47], 0, v[204:205]
	global_load_lds_dwordx4 v[220:221], off
	s_mov_b32 m0, s95
	s_nop 0
	global_load_lds_dwordx4 v[222:223], off
	s_waitcnt vmcnt(8)
	s_waitcnt lgkmcnt(0)
	s_barrier
	s_setprio 1
	s_waitcnt lgkmcnt(0)
	v_mfma_f32_16x16x32_bf16 v[60:63], v[120:123], v[152:155], 0
	v_mfma_f32_16x16x32_bf16 v[56:59], v[128:131], v[152:155], 0
	v_mfma_f32_16x16x32_bf16 v[44:47], v[120:123], v[160:163], 0
	v_mfma_f32_16x16x32_bf16 v[40:43], v[128:131], v[160:163], 0
	v_mfma_f32_16x16x32_bf16 v[28:31], v[120:123], v[176:179], 0
	v_mfma_f32_16x16x32_bf16 v[24:27], v[128:131], v[176:179], 0
	v_mfma_f32_16x16x32_bf16 v[12:15], v[120:123], v[184:187], 0
	v_mfma_f32_16x16x32_bf16 v[8:11], v[128:131], v[184:187], 0
	v_mfma_f32_16x16x32_bf16 v[60:63], v[124:127], v[156:159], v[60:63]
	v_mfma_f32_16x16x32_bf16 v[56:59], v[132:135], v[156:159], v[56:59]
	v_mfma_f32_16x16x32_bf16 v[44:47], v[124:127], v[172:175], v[44:47]
	v_mfma_f32_16x16x32_bf16 v[40:43], v[132:135], v[172:175], v[40:43]
	v_mfma_f32_16x16x32_bf16 v[28:31], v[124:127], v[180:183], v[28:31]
	v_mfma_f32_16x16x32_bf16 v[24:27], v[132:135], v[180:183], v[24:27]
	v_mfma_f32_16x16x32_bf16 v[12:15], v[124:127], v[208:211], v[12:15]
	v_mfma_f32_16x16x32_bf16 v[8:11], v[132:135], v[208:211], v[8:11]
	s_setprio 0
	s_setprio 1
	v_mfma_f32_16x16x32_bf16 v[52:55], v[136:139], v[152:155], 0
	v_mfma_f32_16x16x32_bf16 v[48:51], v[144:147], v[152:155], 0
	v_mfma_f32_16x16x32_bf16 v[36:39], v[136:139], v[160:163], 0
	v_mfma_f32_16x16x32_bf16 v[32:35], v[144:147], v[160:163], 0
	v_mfma_f32_16x16x32_bf16 v[20:23], v[136:139], v[176:179], 0
	v_mfma_f32_16x16x32_bf16 v[16:19], v[144:147], v[176:179], 0
	v_mfma_f32_16x16x32_bf16 v[4:7], v[136:139], v[184:187], 0
	v_mfma_f32_16x16x32_bf16 v[0:3], v[144:147], v[184:187], 0
	v_mfma_f32_16x16x32_bf16 v[52:55], v[140:143], v[156:159], v[52:55]
	v_mfma_f32_16x16x32_bf16 v[48:51], v[148:151], v[156:159], v[48:51]
	v_mfma_f32_16x16x32_bf16 v[36:39], v[140:143], v[172:175], v[36:39]
	v_mfma_f32_16x16x32_bf16 v[32:35], v[148:151], v[172:175], v[32:35]
	v_mfma_f32_16x16x32_bf16 v[20:23], v[140:143], v[180:183], v[20:23]
	v_mfma_f32_16x16x32_bf16 v[16:19], v[148:151], v[180:183], v[16:19]
	v_mfma_f32_16x16x32_bf16 v[4:7], v[140:143], v[208:211], v[4:7]
	v_mfma_f32_16x16x32_bf16 v[0:3], v[148:151], v[208:211], v[0:3]
	s_setprio 0
	s_barrier
	s_add_i32 s3, 0, 0x18000
	s_add_i32 s33, 0, 0x1c000
	v_add_u32_e32 v132, s3, v234
	v_add_u32_e32 v148, s33, v234
	ds_read_b128 v[120:123], v132
	ds_read_b128 v[124:127], v132 offset:1024
	ds_read_b128 v[128:131], v132 offset:2048
	ds_read_b128 v[132:135], v132 offset:3072
	ds_read_b128 v[136:139], v148
	ds_read_b128 v[140:143], v148 offset:1024
	ds_read_b128 v[144:147], v148 offset:2048
	ds_read_b128 v[148:151], v148 offset:3072
	s_add_u32 s36, s46, s92
	s_addc_u32 s37, s47, 0
	s_mov_b32 m0, s96
	v_lshl_add_u64 v[224:225], s[36:37], 0, v[202:203]
	ds_read_b128 v[152:155], v248 offset:32768
	ds_read_b128 v[156:159], v248 offset:33792
	ds_read_b128 v[160:163], v248 offset:34816
	ds_read_b128 v[172:175], v248 offset:35840
	ds_read_b128 v[176:179], v248 offset:36864
	ds_read_b128 v[180:183], v248 offset:37888
	ds_read_b128 v[184:187], v248 offset:38912
	ds_read_b128 v[208:211], v248 offset:39936
	global_load_lds_dwordx4 v[224:225], off
	v_lshl_add_u64 v[224:225], s[36:37], 0, v[204:205]
	s_mov_b32 m0, s97
	s_nop 0
	global_load_lds_dwordx4 v[224:225], off
	s_waitcnt vmcnt(8)
	s_waitcnt lgkmcnt(0)
	s_barrier
	s_setprio 1
	s_waitcnt lgkmcnt(0)
	v_mfma_f32_16x16x32_bf16 v[168:171], v[120:123], v[152:155], v[168:171]
	v_mfma_f32_16x16x32_bf16 v[164:167], v[128:131], v[152:155], v[164:167]
	v_mfma_f32_16x16x32_bf16 v[108:111], v[120:123], v[160:163], v[108:111]
	v_mfma_f32_16x16x32_bf16 v[104:107], v[128:131], v[160:163], v[104:107]
	v_mfma_f32_16x16x32_bf16 v[92:95], v[120:123], v[176:179], v[92:95]
	v_mfma_f32_16x16x32_bf16 v[88:91], v[128:131], v[176:179], v[88:91]
	v_mfma_f32_16x16x32_bf16 v[76:79], v[120:123], v[184:187], v[76:79]
	v_mfma_f32_16x16x32_bf16 v[72:75], v[128:131], v[184:187], v[72:75]
	v_mfma_f32_16x16x32_bf16 v[168:171], v[124:127], v[156:159], v[168:171]
	v_mfma_f32_16x16x32_bf16 v[164:167], v[132:135], v[156:159], v[164:167]
	v_mfma_f32_16x16x32_bf16 v[108:111], v[124:127], v[172:175], v[108:111]
	v_mfma_f32_16x16x32_bf16 v[104:107], v[132:135], v[172:175], v[104:107]
	v_mfma_f32_16x16x32_bf16 v[92:95], v[124:127], v[180:183], v[92:95]
	v_mfma_f32_16x16x32_bf16 v[88:91], v[132:135], v[180:183], v[88:91]
	v_mfma_f32_16x16x32_bf16 v[76:79], v[124:127], v[208:211], v[76:79]
	v_mfma_f32_16x16x32_bf16 v[72:75], v[132:135], v[208:211], v[72:75]
	s_setprio 0
	s_setprio 1
	v_mfma_f32_16x16x32_bf16 v[116:119], v[136:139], v[152:155], v[116:119]
	v_mfma_f32_16x16x32_bf16 v[112:115], v[144:147], v[152:155], v[112:115]
	v_mfma_f32_16x16x32_bf16 v[100:103], v[136:139], v[160:163], v[100:103]
	v_mfma_f32_16x16x32_bf16 v[96:99], v[144:147], v[160:163], v[96:99]
	v_mfma_f32_16x16x32_bf16 v[84:87], v[136:139], v[176:179], v[84:87]
	v_mfma_f32_16x16x32_bf16 v[80:83], v[144:147], v[176:179], v[80:83]
	v_mfma_f32_16x16x32_bf16 v[68:71], v[136:139], v[184:187], v[68:71]
	v_mfma_f32_16x16x32_bf16 v[64:67], v[144:147], v[184:187], v[64:67]
	v_mfma_f32_16x16x32_bf16 v[116:119], v[140:143], v[156:159], v[116:119]
	v_mfma_f32_16x16x32_bf16 v[112:115], v[148:151], v[156:159], v[112:115]
	v_mfma_f32_16x16x32_bf16 v[100:103], v[140:143], v[172:175], v[100:103]
	v_mfma_f32_16x16x32_bf16 v[96:99], v[148:151], v[172:175], v[96:99]
	v_mfma_f32_16x16x32_bf16 v[84:87], v[140:143], v[180:183], v[84:87]
	v_mfma_f32_16x16x32_bf16 v[80:83], v[148:151], v[180:183], v[80:83]
	v_mfma_f32_16x16x32_bf16 v[68:71], v[140:143], v[208:211], v[68:71]
	v_mfma_f32_16x16x32_bf16 v[64:67], v[148:151], v[208:211], v[64:67]
	s_setprio 0
	s_barrier
	s_add_i32 s3, s3, s89
	v_lshl_add_u64 v[212:213], v[212:213], 0, s[72:73]
	s_mov_b32 m0, s3
	ds_read_b128 v[152:155], v248 offset:49152
	ds_read_b128 v[156:159], v248 offset:50176
	ds_read_b128 v[160:163], v248 offset:51200
	ds_read_b128 v[172:175], v248 offset:52224
	ds_read_b128 v[176:179], v248 offset:53248
	ds_read_b128 v[180:183], v248 offset:54272
	ds_read_b128 v[184:187], v248 offset:55296
	ds_read_b128 v[208:211], v248 offset:56320
	global_load_lds_dwordx4 v[212:213], off
	v_lshl_add_u64 v[212:213], v[214:215], 0, s[72:73]
	s_add_i32 m0, s3, 0x2000
	s_add_i32 s3, s33, s89
	global_load_lds_dwordx4 v[212:213], off
	v_lshl_add_u64 v[212:213], v[216:217], 0, s[72:73]
	s_mov_b32 m0, s3
	s_nop 0
	global_load_lds_dwordx4 v[212:213], off
	v_lshl_add_u64 v[212:213], v[218:219], 0, s[72:73]
	s_add_i32 m0, s3, 0x2000
	s_nop 0
	global_load_lds_dwordx4 v[212:213], off
	v_lshl_add_u64 v[212:213], v[220:221], 0, s[72:73]
	s_mov_b32 m0, s76
	s_nop 0
	global_load_lds_dwordx4 v[212:213], off
	v_lshl_add_u64 v[212:213], v[222:223], 0, s[72:73]
	s_mov_b32 m0, s77
	s_nop 0
	global_load_lds_dwordx4 v[212:213], off
	s_waitcnt vmcnt(8)
	s_waitcnt lgkmcnt(0)
	s_barrier
	s_setprio 1
	s_waitcnt lgkmcnt(0)
	v_mfma_f32_16x16x32_bf16 v[60:63], v[120:123], v[152:155], v[60:63]
	v_mfma_f32_16x16x32_bf16 v[56:59], v[128:131], v[152:155], v[56:59]
	v_mfma_f32_16x16x32_bf16 v[44:47], v[120:123], v[160:163], v[44:47]
	v_mfma_f32_16x16x32_bf16 v[40:43], v[128:131], v[160:163], v[40:43]
	v_mfma_f32_16x16x32_bf16 v[28:31], v[120:123], v[176:179], v[28:31]
	v_mfma_f32_16x16x32_bf16 v[24:27], v[128:131], v[176:179], v[24:27]
	v_mfma_f32_16x16x32_bf16 v[12:15], v[120:123], v[184:187], v[12:15]
	v_mfma_f32_16x16x32_bf16 v[8:11], v[128:131], v[184:187], v[8:11]
	v_mfma_f32_16x16x32_bf16 v[60:63], v[124:127], v[156:159], v[60:63]
	v_mfma_f32_16x16x32_bf16 v[56:59], v[132:135], v[156:159], v[56:59]
	v_mfma_f32_16x16x32_bf16 v[44:47], v[124:127], v[172:175], v[44:47]
	v_mfma_f32_16x16x32_bf16 v[40:43], v[132:135], v[172:175], v[40:43]
	v_mfma_f32_16x16x32_bf16 v[28:31], v[124:127], v[180:183], v[28:31]
	v_mfma_f32_16x16x32_bf16 v[24:27], v[132:135], v[180:183], v[24:27]
	v_mfma_f32_16x16x32_bf16 v[12:15], v[124:127], v[208:211], v[12:15]
	v_mfma_f32_16x16x32_bf16 v[8:11], v[132:135], v[208:211], v[8:11]
	s_setprio 0
	s_setprio 1
	v_mfma_f32_16x16x32_bf16 v[52:55], v[136:139], v[152:155], v[52:55]
	v_mfma_f32_16x16x32_bf16 v[48:51], v[144:147], v[152:155], v[48:51]
	v_mfma_f32_16x16x32_bf16 v[36:39], v[136:139], v[160:163], v[36:39]
	v_mfma_f32_16x16x32_bf16 v[32:35], v[144:147], v[160:163], v[32:35]
	v_mfma_f32_16x16x32_bf16 v[20:23], v[136:139], v[176:179], v[20:23]
	v_mfma_f32_16x16x32_bf16 v[16:19], v[144:147], v[176:179], v[16:19]
	v_mfma_f32_16x16x32_bf16 v[4:7], v[136:139], v[184:187], v[4:7]
	v_mfma_f32_16x16x32_bf16 v[0:3], v[144:147], v[184:187], v[0:3]
	v_mfma_f32_16x16x32_bf16 v[52:55], v[140:143], v[156:159], v[52:55]
	v_mfma_f32_16x16x32_bf16 v[48:51], v[148:151], v[156:159], v[48:51]
	v_mfma_f32_16x16x32_bf16 v[36:39], v[140:143], v[172:175], v[36:39]
	v_mfma_f32_16x16x32_bf16 v[32:35], v[148:151], v[172:175], v[32:35]
	v_mfma_f32_16x16x32_bf16 v[20:23], v[140:143], v[180:183], v[20:23]
	v_mfma_f32_16x16x32_bf16 v[16:19], v[148:151], v[180:183], v[16:19]
	v_mfma_f32_16x16x32_bf16 v[4:7], v[140:143], v[208:211], v[4:7]
	v_mfma_f32_16x16x32_bf16 v[0:3], v[148:151], v[208:211], v[0:3]
	s_setprio 0
	s_barrier
	s_add_i32 s86, s86, 2
	s_cmp_ge_u32 s86, s98
	s_mov_b64 s[36:37], s[38:39]
	s_cbranch_scc1 .Lpeel_exit_resid
.LBB0_490:
	s_add_u32 s38, s36, 0x100
	s_addc_u32 s39, s37, 0
	v_mov_b64_e32 v[120:121], s[24:25]
	v_cmp_ge_u64_e32 vcc, s[38:39], v[120:121]
	s_and_b64 s[46:47], vcc, exec
	s_cselect_b32 s47, s24, 0
	s_cselect_b32 s46, 0, 0
	s_sub_u32 s38, s38, s47
	s_subb_u32 s39, s39, s46
	s_sub_u32 s47, s36, s47
	s_subb_u32 s46, s37, s46
	s_add_u32 vcc_lo, s34, s47
	s_addc_u32 vcc_hi, s35, s46
	s_add_u32 vcc_lo, vcc_lo, 0x100
	s_addc_u32 vcc_hi, vcc_hi, 0
	s_add_u32 s47, s30, s47
	s_addc_u32 s46, s31, s46
	s_add_u32 s69, s47, 0x100
	s_addc_u32 s3, s46, 0
	s_add_i32 s33, 0, 0x10000
	s_cmp_eq_u32 s99, s86
	s_cselect_b32 s47, s11, vcc_hi
	s_cselect_b32 s46, s10, vcc_lo
	s_cselect_b32 vcc_hi, s29, s3
	s_cselect_b32 vcc_lo, s28, s69
	s_add_i32 s3, 0, 0x14000
	v_add_u32_e32 v132, s33, v234
	v_add_u32_e32 v148, s3, v234
	ds_read_b128 v[120:123], v132
	ds_read_b128 v[124:127], v132 offset:1024
	ds_read_b128 v[128:131], v132 offset:2048
	ds_read_b128 v[132:135], v132 offset:3072
	ds_read_b128 v[136:139], v148
	ds_read_b128 v[140:143], v148 offset:1024
	ds_read_b128 v[144:147], v148 offset:2048
	ds_read_b128 v[148:151], v148 offset:3072
	s_add_u32 s36, s0, s36
	s_addc_u32 s37, s43, s37
	v_lshl_add_u64 v[212:213], s[36:37], 0, v[202:203]
	v_lshl_add_u64 v[212:213], v[212:213], 0, s[72:73]
	s_add_i32 m0, s94, 0xc000
	ds_read_b128 v[152:155], v248
	ds_read_b128 v[156:159], v248 offset:1024
	ds_read_b128 v[160:163], v248 offset:2048
	ds_read_b128 v[172:175], v248 offset:3072
	ds_read_b128 v[176:179], v248 offset:4096
	ds_read_b128 v[180:183], v248 offset:5120
	ds_read_b128 v[184:187], v248 offset:6144
	ds_read_b128 v[208:211], v248 offset:7168
	global_load_lds_dwordx4 v[212:213], off
	v_lshl_add_u64 v[212:213], s[36:37], 0, v[204:205]
	v_lshl_add_u64 v[212:213], v[212:213], 0, s[72:73]
	s_add_i32 m0, s94, 0xe000
	s_nop 0
	global_load_lds_dwordx4 v[212:213], off
	s_waitcnt vmcnt(8)
	s_waitcnt lgkmcnt(0)
	s_barrier
	s_setprio 1
	s_waitcnt lgkmcnt(0)
	v_mfma_f32_16x16x32_bf16 v[168:171], v[120:123], v[152:155], v[168:171]
	v_mfma_f32_16x16x32_bf16 v[164:167], v[128:131], v[152:155], v[164:167]
	v_mfma_f32_16x16x32_bf16 v[108:111], v[120:123], v[160:163], v[108:111]
	v_mfma_f32_16x16x32_bf16 v[104:107], v[128:131], v[160:163], v[104:107]
	v_mfma_f32_16x16x32_bf16 v[92:95], v[120:123], v[176:179], v[92:95]
	v_mfma_f32_16x16x32_bf16 v[88:91], v[128:131], v[176:179], v[88:91]
	v_mfma_f32_16x16x32_bf16 v[76:79], v[120:123], v[184:187], v[76:79]
	v_mfma_f32_16x16x32_bf16 v[72:75], v[128:131], v[184:187], v[72:75]
	v_mfma_f32_16x16x32_bf16 v[168:171], v[124:127], v[156:159], v[168:171]
	v_mfma_f32_16x16x32_bf16 v[164:167], v[132:135], v[156:159], v[164:167]
	v_mfma_f32_16x16x32_bf16 v[108:111], v[124:127], v[172:175], v[108:111]
	v_mfma_f32_16x16x32_bf16 v[104:107], v[132:135], v[172:175], v[104:107]
	v_mfma_f32_16x16x32_bf16 v[92:95], v[124:127], v[180:183], v[92:95]
	v_mfma_f32_16x16x32_bf16 v[88:91], v[132:135], v[180:183], v[88:91]
	v_mfma_f32_16x16x32_bf16 v[76:79], v[124:127], v[208:211], v[76:79]
	v_mfma_f32_16x16x32_bf16 v[72:75], v[132:135], v[208:211], v[72:75]
	s_setprio 0
	s_setprio 1
	v_mfma_f32_16x16x32_bf16 v[116:119], v[136:139], v[152:155], v[116:119]
	v_mfma_f32_16x16x32_bf16 v[112:115], v[144:147], v[152:155], v[112:115]
	v_mfma_f32_16x16x32_bf16 v[100:103], v[136:139], v[160:163], v[100:103]
	v_mfma_f32_16x16x32_bf16 v[96:99], v[144:147], v[160:163], v[96:99]
	v_mfma_f32_16x16x32_bf16 v[84:87], v[136:139], v[176:179], v[84:87]
	v_mfma_f32_16x16x32_bf16 v[80:83], v[144:147], v[176:179], v[80:83]
	v_mfma_f32_16x16x32_bf16 v[68:71], v[136:139], v[184:187], v[68:71]
	v_mfma_f32_16x16x32_bf16 v[64:67], v[144:147], v[184:187], v[64:67]
	v_mfma_f32_16x16x32_bf16 v[116:119], v[140:143], v[156:159], v[116:119]
	v_mfma_f32_16x16x32_bf16 v[112:115], v[148:151], v[156:159], v[112:115]
	v_mfma_f32_16x16x32_bf16 v[100:103], v[140:143], v[172:175], v[100:103]
	v_mfma_f32_16x16x32_bf16 v[96:99], v[148:151], v[172:175], v[96:99]
	v_mfma_f32_16x16x32_bf16 v[84:87], v[140:143], v[180:183], v[84:87]
	v_mfma_f32_16x16x32_bf16 v[80:83], v[148:151], v[180:183], v[80:83]
	v_mfma_f32_16x16x32_bf16 v[68:71], v[140:143], v[208:211], v[68:71]
	v_mfma_f32_16x16x32_bf16 v[64:67], v[148:151], v[208:211], v[64:67]
	s_setprio 0
	s_barrier
	s_add_i32 s33, s33, s89
	v_lshl_add_u64 v[212:213], vcc, 0, v[188:189]
	s_mov_b32 m0, s33
	ds_read_b128 v[152:155], v248 offset:16384
	ds_read_b128 v[156:159], v248 offset:17408
	ds_read_b128 v[160:163], v248 offset:18432
	ds_read_b128 v[172:175], v248 offset:19456
	ds_read_b128 v[176:179], v248 offset:20480
	ds_read_b128 v[180:183], v248 offset:21504
	ds_read_b128 v[184:187], v248 offset:22528
	ds_read_b128 v[208:211], v248 offset:23552
	global_load_lds_dwordx4 v[212:213], off
	s_add_i32 m0, s33, 0x2000
	s_add_u32 s36, vcc_lo, s92
	v_lshl_add_u64 v[214:215], vcc, 0, v[206:207]
	s_addc_u32 s37, vcc_hi, 0
	s_add_i32 s3, s3, s89
	global_load_lds_dwordx4 v[214:215], off
	v_lshl_add_u64 v[216:217], s[36:37], 0, v[188:189]
	s_mov_b32 m0, s3
	v_lshl_add_u64 v[218:219], s[36:37], 0, v[206:207]
	global_load_lds_dwordx4 v[216:217], off
	s_add_i32 m0, s3, 0x2000
	v_lshl_add_u64 v[220:221], s[46:47], 0, v[202:203]
	global_load_lds_dwordx4 v[218:219], off
	s_mov_b32 m0, s94
	v_lshl_add_u64 v[222:223], s[46:47], 0, v[204:205]
	global_load_lds_dwordx4 v[220:221], off
	s_mov_b32 m0, s95
	s_nop 0
	global_load_lds_dwordx4 v[222:223], off
	s_waitcnt vmcnt(8)
	s_waitcnt lgkmcnt(0)
	s_barrier
	s_setprio 1
	s_waitcnt lgkmcnt(0)
	v_mfma_f32_16x16x32_bf16 v[60:63], v[120:123], v[152:155], v[60:63]
	v_mfma_f32_16x16x32_bf16 v[56:59], v[128:131], v[152:155], v[56:59]
	v_mfma_f32_16x16x32_bf16 v[44:47], v[120:123], v[160:163], v[44:47]
	v_mfma_f32_16x16x32_bf16 v[40:43], v[128:131], v[160:163], v[40:43]
	v_mfma_f32_16x16x32_bf16 v[28:31], v[120:123], v[176:179], v[28:31]
	v_mfma_f32_16x16x32_bf16 v[24:27], v[128:131], v[176:179], v[24:27]
	v_mfma_f32_16x16x32_bf16 v[12:15], v[120:123], v[184:187], v[12:15]
	v_mfma_f32_16x16x32_bf16 v[8:11], v[128:131], v[184:187], v[8:11]
	v_mfma_f32_16x16x32_bf16 v[60:63], v[124:127], v[156:159], v[60:63]
	v_mfma_f32_16x16x32_bf16 v[56:59], v[132:135], v[156:159], v[56:59]
	v_mfma_f32_16x16x32_bf16 v[44:47], v[124:127], v[172:175], v[44:47]
	v_mfma_f32_16x16x32_bf16 v[40:43], v[132:135], v[172:175], v[40:43]
	v_mfma_f32_16x16x32_bf16 v[28:31], v[124:127], v[180:183], v[28:31]
	v_mfma_f32_16x16x32_bf16 v[24:27], v[132:135], v[180:183], v[24:27]
	v_mfma_f32_16x16x32_bf16 v[12:15], v[124:127], v[208:211], v[12:15]
	v_mfma_f32_16x16x32_bf16 v[8:11], v[132:135], v[208:211], v[8:11]
	s_setprio 0
	s_setprio 1
	v_mfma_f32_16x16x32_bf16 v[52:55], v[136:139], v[152:155], v[52:55]
	v_mfma_f32_16x16x32_bf16 v[48:51], v[144:147], v[152:155], v[48:51]
	v_mfma_f32_16x16x32_bf16 v[36:39], v[136:139], v[160:163], v[36:39]
	v_mfma_f32_16x16x32_bf16 v[32:35], v[144:147], v[160:163], v[32:35]
	v_mfma_f32_16x16x32_bf16 v[20:23], v[136:139], v[176:179], v[20:23]
	v_mfma_f32_16x16x32_bf16 v[16:19], v[144:147], v[176:179], v[16:19]
	v_mfma_f32_16x16x32_bf16 v[4:7], v[136:139], v[184:187], v[4:7]
	v_mfma_f32_16x16x32_bf16 v[0:3], v[144:147], v[184:187], v[0:3]
	v_mfma_f32_16x16x32_bf16 v[52:55], v[140:143], v[156:159], v[52:55]
	v_mfma_f32_16x16x32_bf16 v[48:51], v[148:151], v[156:159], v[48:51]
	v_mfma_f32_16x16x32_bf16 v[36:39], v[140:143], v[172:175], v[36:39]
	v_mfma_f32_16x16x32_bf16 v[32:35], v[148:151], v[172:175], v[32:35]
	v_mfma_f32_16x16x32_bf16 v[20:23], v[140:143], v[180:183], v[20:23]
	v_mfma_f32_16x16x32_bf16 v[16:19], v[148:151], v[180:183], v[16:19]
	v_mfma_f32_16x16x32_bf16 v[4:7], v[140:143], v[208:211], v[4:7]
	v_mfma_f32_16x16x32_bf16 v[0:3], v[148:151], v[208:211], v[0:3]
	s_setprio 0
	s_barrier
	s_add_i32 s3, 0, 0x18000
	s_add_i32 s33, 0, 0x1c000
	v_add_u32_e32 v132, s3, v234
	v_add_u32_e32 v148, s33, v234
	ds_read_b128 v[120:123], v132
	ds_read_b128 v[124:127], v132 offset:1024
	ds_read_b128 v[128:131], v132 offset:2048
	ds_read_b128 v[132:135], v132 offset:3072
	ds_read_b128 v[136:139], v148
	ds_read_b128 v[140:143], v148 offset:1024
	ds_read_b128 v[144:147], v148 offset:2048
	ds_read_b128 v[148:151], v148 offset:3072
	s_add_u32 s36, s46, s92
	s_addc_u32 s37, s47, 0
	s_mov_b32 m0, s96
	v_lshl_add_u64 v[224:225], s[36:37], 0, v[202:203]
	ds_read_b128 v[152:155], v248 offset:32768
	ds_read_b128 v[156:159], v248 offset:33792
	ds_read_b128 v[160:163], v248 offset:34816
	ds_read_b128 v[172:175], v248 offset:35840
	ds_read_b128 v[176:179], v248 offset:36864
	ds_read_b128 v[180:183], v248 offset:37888
	ds_read_b128 v[184:187], v248 offset:38912
	ds_read_b128 v[208:211], v248 offset:39936
	global_load_lds_dwordx4 v[224:225], off
	v_lshl_add_u64 v[224:225], s[36:37], 0, v[204:205]
	s_mov_b32 m0, s97
	s_nop 0
	global_load_lds_dwordx4 v[224:225], off
	s_waitcnt vmcnt(8)
	s_waitcnt lgkmcnt(0)
	s_barrier
	s_setprio 1
	s_waitcnt lgkmcnt(0)
	v_mfma_f32_16x16x32_bf16 v[168:171], v[120:123], v[152:155], v[168:171]
	v_mfma_f32_16x16x32_bf16 v[164:167], v[128:131], v[152:155], v[164:167]
	v_mfma_f32_16x16x32_bf16 v[108:111], v[120:123], v[160:163], v[108:111]
	v_mfma_f32_16x16x32_bf16 v[104:107], v[128:131], v[160:163], v[104:107]
	v_mfma_f32_16x16x32_bf16 v[92:95], v[120:123], v[176:179], v[92:95]
	v_mfma_f32_16x16x32_bf16 v[88:91], v[128:131], v[176:179], v[88:91]
	v_mfma_f32_16x16x32_bf16 v[76:79], v[120:123], v[184:187], v[76:79]
	v_mfma_f32_16x16x32_bf16 v[72:75], v[128:131], v[184:187], v[72:75]
	v_mfma_f32_16x16x32_bf16 v[168:171], v[124:127], v[156:159], v[168:171]
	v_mfma_f32_16x16x32_bf16 v[164:167], v[132:135], v[156:159], v[164:167]
	v_mfma_f32_16x16x32_bf16 v[108:111], v[124:127], v[172:175], v[108:111]
	v_mfma_f32_16x16x32_bf16 v[104:107], v[132:135], v[172:175], v[104:107]
	v_mfma_f32_16x16x32_bf16 v[92:95], v[124:127], v[180:183], v[92:95]
	v_mfma_f32_16x16x32_bf16 v[88:91], v[132:135], v[180:183], v[88:91]
	v_mfma_f32_16x16x32_bf16 v[76:79], v[124:127], v[208:211], v[76:79]
	v_mfma_f32_16x16x32_bf16 v[72:75], v[132:135], v[208:211], v[72:75]
	s_setprio 0
	s_setprio 1
	v_mfma_f32_16x16x32_bf16 v[116:119], v[136:139], v[152:155], v[116:119]
	v_mfma_f32_16x16x32_bf16 v[112:115], v[144:147], v[152:155], v[112:115]
	v_mfma_f32_16x16x32_bf16 v[100:103], v[136:139], v[160:163], v[100:103]
	v_mfma_f32_16x16x32_bf16 v[96:99], v[144:147], v[160:163], v[96:99]
	v_mfma_f32_16x16x32_bf16 v[84:87], v[136:139], v[176:179], v[84:87]
	v_mfma_f32_16x16x32_bf16 v[80:83], v[144:147], v[176:179], v[80:83]
	v_mfma_f32_16x16x32_bf16 v[68:71], v[136:139], v[184:187], v[68:71]
	v_mfma_f32_16x16x32_bf16 v[64:67], v[144:147], v[184:187], v[64:67]
	v_mfma_f32_16x16x32_bf16 v[116:119], v[140:143], v[156:159], v[116:119]
	v_mfma_f32_16x16x32_bf16 v[112:115], v[148:151], v[156:159], v[112:115]
	v_mfma_f32_16x16x32_bf16 v[100:103], v[140:143], v[172:175], v[100:103]
	v_mfma_f32_16x16x32_bf16 v[96:99], v[148:151], v[172:175], v[96:99]
	v_mfma_f32_16x16x32_bf16 v[84:87], v[140:143], v[180:183], v[84:87]
	v_mfma_f32_16x16x32_bf16 v[80:83], v[148:151], v[180:183], v[80:83]
	v_mfma_f32_16x16x32_bf16 v[68:71], v[140:143], v[208:211], v[68:71]
	v_mfma_f32_16x16x32_bf16 v[64:67], v[148:151], v[208:211], v[64:67]
	s_setprio 0
	s_barrier
	s_add_i32 s3, s3, s89
	v_lshl_add_u64 v[212:213], v[212:213], 0, s[72:73]
	s_mov_b32 m0, s3
	ds_read_b128 v[152:155], v248 offset:49152
	ds_read_b128 v[156:159], v248 offset:50176
	ds_read_b128 v[160:163], v248 offset:51200
	ds_read_b128 v[172:175], v248 offset:52224
	ds_read_b128 v[176:179], v248 offset:53248
	ds_read_b128 v[180:183], v248 offset:54272
	ds_read_b128 v[184:187], v248 offset:55296
	ds_read_b128 v[208:211], v248 offset:56320
	global_load_lds_dwordx4 v[212:213], off
	v_lshl_add_u64 v[212:213], v[214:215], 0, s[72:73]
	s_add_i32 m0, s3, 0x2000
	s_add_i32 s3, s33, s89
	global_load_lds_dwordx4 v[212:213], off
	v_lshl_add_u64 v[212:213], v[216:217], 0, s[72:73]
	s_mov_b32 m0, s3
	s_nop 0
	global_load_lds_dwordx4 v[212:213], off
	v_lshl_add_u64 v[212:213], v[218:219], 0, s[72:73]
	s_add_i32 m0, s3, 0x2000
	s_nop 0
	global_load_lds_dwordx4 v[212:213], off
	v_lshl_add_u64 v[212:213], v[220:221], 0, s[72:73]
	s_mov_b32 m0, s76
	s_nop 0
	global_load_lds_dwordx4 v[212:213], off
	v_lshl_add_u64 v[212:213], v[222:223], 0, s[72:73]
	s_mov_b32 m0, s77
	s_nop 0
	global_load_lds_dwordx4 v[212:213], off
	s_waitcnt vmcnt(8)
	s_waitcnt lgkmcnt(0)
	s_barrier
	s_setprio 1
	s_waitcnt lgkmcnt(0)
	v_mfma_f32_16x16x32_bf16 v[60:63], v[120:123], v[152:155], v[60:63]
	v_mfma_f32_16x16x32_bf16 v[56:59], v[128:131], v[152:155], v[56:59]
	v_mfma_f32_16x16x32_bf16 v[44:47], v[120:123], v[160:163], v[44:47]
	v_mfma_f32_16x16x32_bf16 v[40:43], v[128:131], v[160:163], v[40:43]
	v_mfma_f32_16x16x32_bf16 v[28:31], v[120:123], v[176:179], v[28:31]
	v_mfma_f32_16x16x32_bf16 v[24:27], v[128:131], v[176:179], v[24:27]
	v_mfma_f32_16x16x32_bf16 v[12:15], v[120:123], v[184:187], v[12:15]
	v_mfma_f32_16x16x32_bf16 v[8:11], v[128:131], v[184:187], v[8:11]
	v_mfma_f32_16x16x32_bf16 v[60:63], v[124:127], v[156:159], v[60:63]
	v_mfma_f32_16x16x32_bf16 v[56:59], v[132:135], v[156:159], v[56:59]
	v_mfma_f32_16x16x32_bf16 v[44:47], v[124:127], v[172:175], v[44:47]
	v_mfma_f32_16x16x32_bf16 v[40:43], v[132:135], v[172:175], v[40:43]
	v_mfma_f32_16x16x32_bf16 v[28:31], v[124:127], v[180:183], v[28:31]
	v_mfma_f32_16x16x32_bf16 v[24:27], v[132:135], v[180:183], v[24:27]
	v_mfma_f32_16x16x32_bf16 v[12:15], v[124:127], v[208:211], v[12:15]
	v_mfma_f32_16x16x32_bf16 v[8:11], v[132:135], v[208:211], v[8:11]
	s_setprio 0
	s_setprio 1
	v_mfma_f32_16x16x32_bf16 v[52:55], v[136:139], v[152:155], v[52:55]
	v_mfma_f32_16x16x32_bf16 v[48:51], v[144:147], v[152:155], v[48:51]
	v_mfma_f32_16x16x32_bf16 v[36:39], v[136:139], v[160:163], v[36:39]
	v_mfma_f32_16x16x32_bf16 v[32:35], v[144:147], v[160:163], v[32:35]
	v_mfma_f32_16x16x32_bf16 v[20:23], v[136:139], v[176:179], v[20:23]
	v_mfma_f32_16x16x32_bf16 v[16:19], v[144:147], v[176:179], v[16:19]
	v_mfma_f32_16x16x32_bf16 v[4:7], v[136:139], v[184:187], v[4:7]
	v_mfma_f32_16x16x32_bf16 v[0:3], v[144:147], v[184:187], v[0:3]
	v_mfma_f32_16x16x32_bf16 v[52:55], v[140:143], v[156:159], v[52:55]
	v_mfma_f32_16x16x32_bf16 v[48:51], v[148:151], v[156:159], v[48:51]
	v_mfma_f32_16x16x32_bf16 v[36:39], v[140:143], v[172:175], v[36:39]
	v_mfma_f32_16x16x32_bf16 v[32:35], v[148:151], v[172:175], v[32:35]
	v_mfma_f32_16x16x32_bf16 v[20:23], v[140:143], v[180:183], v[20:23]
	v_mfma_f32_16x16x32_bf16 v[16:19], v[148:151], v[180:183], v[16:19]
	v_mfma_f32_16x16x32_bf16 v[4:7], v[140:143], v[208:211], v[4:7]
	v_mfma_f32_16x16x32_bf16 v[0:3], v[148:151], v[208:211], v[0:3]
	s_setprio 0
	s_barrier
	s_add_i32 s86, s86, 2
	s_cmp_ge_u32 s86, s98
	s_mov_b64 s[36:37], s[38:39]
	s_cbranch_scc0 .LBB0_490
.Lpeel_exit_resid:
	s_and_b64 vcc, exec, s[26:27]
	s_cbranch_vccz .LBB0_493
	s_barrier
.LBB0_493:
	s_lshl_b32 s17, s17, 8
	v_lshl_or_b32 v208, s16, 8, v236
	v_add_u32_e32 v120, s17, v233
	v_ashrrev_i32_e32 v209, 31, v208
	v_lshlrev_b64 v[224:225], 1, v[208:209]
	v_ashrrev_i32_e32 v121, 31, v120
	v_lshl_add_u64 v[122:123], s[20:21], 0, v[224:225]
	v_lshlrev_b64 v[226:227], 11, v[120:121]
	v_lshl_add_u64 v[124:125], v[122:123], 0, v[226:227]
	global_load_dwordx4 v[250:253], v[124:125], off
	global_load_dwordx4 v[184:187], v[124:125], off offset:256
	v_or_b32_e32 v124, 16, v120
	v_ashrrev_i32_e32 v125, 31, v124
	v_lshlrev_b64 v[222:223], 11, v[124:125]
	v_lshl_add_u64 v[124:125], v[122:123], 0, v[222:223]
	global_load_dwordx4 v[180:183], v[124:125], off
	global_load_dwordx4 v[176:179], v[124:125], off offset:256
	v_or_b32_e32 v124, 32, v120
	v_or_b32_e32 v120, 48, v120
	v_ashrrev_i32_e32 v125, 31, v124
	v_ashrrev_i32_e32 v121, 31, v120
	v_lshlrev_b64 v[220:221], 11, v[124:125]
	v_lshlrev_b64 v[218:219], 11, v[120:121]
	s_mov_b64 s[2:3], 0x40000
	v_lshl_add_u64 v[124:125], v[122:123], 0, v[220:221]
	v_lshl_add_u64 v[120:121], v[122:123], 0, v[218:219]
	v_lshl_add_u64 v[216:217], v[226:227], 0, s[2:3]
	s_mov_b64 s[30:31], 0x48000
	global_load_dwordx4 v[172:175], v[124:125], off
	global_load_dwordx4 v[160:163], v[124:125], off offset:256
	global_load_dwordx4 v[156:159], v[120:121], off
	global_load_dwordx4 v[152:155], v[120:121], off offset:256
	v_lshl_add_u64 v[120:121], v[122:123], 0, v[216:217]
	v_lshl_add_u64 v[214:215], v[226:227], 0, s[30:31]
	s_mov_b64 s[30:31], 0x50000
	global_load_dwordx4 v[148:151], v[120:121], off
	global_load_dwordx4 v[140:143], v[120:121], off offset:256
	v_lshl_add_u64 v[120:121], v[122:123], 0, v[214:215]
	v_lshl_add_u64 v[212:213], v[226:227], 0, s[30:31]
	s_mov_b64 s[30:31], 0x58000
	global_load_dwordx4 v[144:147], v[120:121], off
	global_load_dwordx4 v[136:139], v[120:121], off offset:256
	v_lshl_add_u64 v[120:121], v[122:123], 0, v[212:213]
	v_lshl_add_u64 v[210:211], v[226:227], 0, s[30:31]
	global_load_dwordx4 v[132:135], v[120:121], off
	global_load_dwordx4 v[128:131], v[120:121], off offset:256
	v_lshl_add_u64 v[120:121], v[122:123], 0, v[210:211]
	global_load_dwordx4 v[124:127], v[120:121], off
	s_nop 0
	global_load_dwordx4 v[120:123], v[120:121], off offset:256
	s_waitcnt vmcnt(0) lgkmcnt(0)
	v_lshlrev_b32_e32 v254, 16, v250
	v_fmac_f32_e32 v254, v235, v168
	v_and_b32_e32 v168, 0xffff0000, v250
	v_fmac_f32_e32 v168, v235, v169
	v_lshlrev_b32_e32 v169, 16, v251
	v_fmac_f32_e32 v169, v235, v170
	v_and_b32_e32 v170, 0xffff0000, v251
	v_fmac_f32_e32 v170, v235, v171
	v_cvt_pk_bf16_f32 v168, v254, v168
	v_cvt_pk_bf16_f32 v169, v169, v170
	v_lshlrev_b32_e32 v170, 16, v252
	v_fmac_f32_e32 v170, v235, v164
	v_and_b32_e32 v164, 0xffff0000, v252
	v_fmac_f32_e32 v164, v235, v165
	v_cvt_pk_bf16_f32 v170, v170, v164
	v_lshlrev_b32_e32 v164, 16, v253
	v_and_b32_e32 v165, 0xffff0000, v253
	v_fmac_f32_e32 v164, v235, v166
	v_fmac_f32_e32 v165, v235, v167
	v_cvt_pk_bf16_f32 v171, v164, v165
	v_lshl_add_u64 v[164:165], s[20:21], 0, v[226:227]
	v_lshl_add_u64 v[164:165], v[164:165], 0, v[224:225]
	v_and_b32_e32 v167, 0xffff0000, v168
	global_store_dwordx4 v[164:165], v[168:171], off
	v_lshlrev_b32_e32 v166, 16, v168
	v_mul_f32_e32 v167, v167, v167
	v_and_b32_e32 v168, 0xffff0000, v169
	v_fmac_f32_e32 v167, v166, v166
	v_lshlrev_b32_e32 v166, 16, v169
	v_mul_f32_e32 v168, v168, v168
	v_fmac_f32_e32 v168, v166, v166
	v_add_f32_e32 v166, v167, v168
	v_and_b32_e32 v168, 0xffff0000, v170
	v_lshlrev_b32_e32 v167, 16, v170
	v_mul_f32_e32 v168, v168, v168
	v_fmac_f32_e32 v168, v167, v167
	v_add_f32_e32 v166, v166, v168
	v_and_b32_e32 v168, 0xffff0000, v171
	v_lshlrev_b32_e32 v167, 16, v171
	v_mul_f32_e32 v168, v168, v168
	v_fmac_f32_e32 v168, v167, v167
	v_lshlrev_b32_e32 v167, 16, v184
	v_fmac_f32_e32 v167, v235, v116
	v_and_b32_e32 v116, 0xffff0000, v184
	v_fmac_f32_e32 v116, v235, v117
	v_lshlrev_b32_e32 v117, 16, v185
	v_fmac_f32_e32 v117, v235, v118
	v_and_b32_e32 v118, 0xffff0000, v185
	v_fmac_f32_e32 v118, v235, v119
	v_cvt_pk_bf16_f32 v116, v167, v116
	v_cvt_pk_bf16_f32 v117, v117, v118
	v_lshlrev_b32_e32 v118, 16, v186
	v_fmac_f32_e32 v118, v235, v112
	v_and_b32_e32 v112, 0xffff0000, v186
	v_fmac_f32_e32 v112, v235, v113
	v_and_b32_e32 v113, 0xffff0000, v187
	v_cvt_pk_bf16_f32 v118, v118, v112
	v_lshlrev_b32_e32 v112, 16, v187
	v_fmac_f32_e32 v113, v235, v115
	v_fmac_f32_e32 v112, v235, v114
	v_cvt_pk_bf16_f32 v119, v112, v113
	v_and_b32_e32 v113, 0xffff0000, v116
	v_lshlrev_b32_e32 v112, 16, v116
	v_mul_f32_e32 v113, v113, v113
	v_and_b32_e32 v114, 0xffff0000, v117
	v_fmac_f32_e32 v113, v112, v112
	v_lshlrev_b32_e32 v112, 16, v117
	v_mul_f32_e32 v114, v114, v114
	v_fmac_f32_e32 v114, v112, v112
	v_add_f32_e32 v112, v113, v114
	v_and_b32_e32 v114, 0xffff0000, v118
	v_lshlrev_b32_e32 v113, 16, v118
	v_mul_f32_e32 v114, v114, v114
	v_fmac_f32_e32 v114, v113, v113
	v_add_f32_e32 v112, v112, v114
	v_and_b32_e32 v114, 0xffff0000, v119
	v_lshlrev_b32_e32 v113, 16, v119
	v_mul_f32_e32 v114, v114, v114
	v_fmac_f32_e32 v114, v113, v113
	v_add_f32_e32 v166, v166, v168
	v_add_f32_e32 v112, v112, v114
	v_add_f32_e32 v112, v166, v112
	ds_bpermute_b32 v113, v237, v112
	global_store_dwordx4 v[164:165], v[116:119], off offset:256
	s_waitcnt lgkmcnt(0)
	v_add_f32_e32 v112, v112, v113
	ds_bpermute_b32 v113, v238, v112
	s_and_saveexec_b64 s[30:31], s[4:5]
	s_cbranch_execz .LBB0_495
	s_waitcnt lgkmcnt(0)
	v_add_f32_e32 v112, v112, v113
	ds_write_b32 v240, v112

.LBB0_527:
	s_ashr_i32 s19, s18, 31
	s_lshl_b64 s[20:21], s[18:19], 19
	s_add_u32 s20, s50, s20
	s_addc_u32 s21, s51, s21
	s_and_b64 s[22:23], s[4:5], exec
	s_cselect_b32 s19, s21, s29
	s_cselect_b32 s25, s20, s28
	s_ashr_i32 s17, s16, 31
	s_lshl_b64 s[22:23], s[16:17], 19
	s_add_u32 s22, s46, s22
	s_addc_u32 s23, s47, s23
	s_and_b64 s[30:31], s[4:5], exec
	s_cselect_b32 s0, s23, s27
	s_cselect_b32 s17, s22, s26
	s_mov_b64 s[30:31], 0
	s_mov_b32 s43, -2
	s_add_u32 s34, s30, 0x100
	s_addc_u32 s35, s31, 0
	s_add_u32 s38, s30, 0xfffff900
	v_cmp_gt_u64_e32 vcc, s[34:35], v[192:193]
	s_addc_u32 s39, s31, -1
	s_and_b64 s[36:37], vcc, exec
	s_cselect_b32 s34, s38, s34
	s_cselect_b32 s35, s39, s35
	s_add_u32 s36, s28, s34
	s_addc_u32 s37, s29, s35
	s_add_u32 s76, s26, s34
	s_addc_u32 s77, s27, s35
	s_add_i32 s86, 0, 0x10000
	s_cmp_eq_u32 s43, 12
	s_cselect_b32 s39, s19, s37
	s_cselect_b32 s38, s25, s36
	v_add_u32_e32 v138, s86, v141
	s_cselect_b32 s37, s0, s77
	s_cselect_b32 s36, s17, s76
	s_add_i32 s76, 0, 0x14000
	ds_read_b128 v[96:99], v138
	ds_read_b128 v[150:153], v138 offset:1024
	ds_read_b128 v[154:157], v138 offset:2048
	ds_read_b128 v[158:161], v138 offset:3072
	v_add_u32_e32 v138, s76, v141
	ds_read_b128 v[162:165], v138
	ds_read_b128 v[166:169], v138 offset:1024
	ds_read_b128 v[170:173], v138 offset:2048
	ds_read_b128 v[174:177], v138 offset:3072
	s_add_u32 s30, s28, s30
	s_addc_u32 s31, s29, s31
	s_add_u32 s30, s30, 0x40080
	s_addc_u32 s31, s31, 0
	v_lshl_add_u64 v[186:187], s[30:31], 0, v[136:137]
	s_add_i32 m0, s60, 0xc000
	ds_read_b128 v[178:181], v149
	ds_read_b128 v[182:185], v149 offset:1024
	ds_read_b128 v[202:205], v149 offset:2048
	ds_read_b128 v[206:209], v149 offset:3072
	ds_read_b128 v[210:213], v149 offset:4096
	ds_read_b128 v[214:217], v149 offset:5120
	ds_read_b128 v[218:221], v149 offset:6144
	ds_read_b128 v[222:225], v149 offset:7168
	global_load_lds_dwordx4 v[186:187], off
	v_lshl_add_u64 v[186:187], s[30:31], 0, v[134:135]
	s_add_i32 m0, s60, 0xe000
	s_nop 0
	global_load_lds_dwordx4 v[186:187], off
	s_waitcnt vmcnt(8)
	s_waitcnt lgkmcnt(0)
	s_barrier
	s_setprio 1
	s_waitcnt lgkmcnt(0)
	v_mfma_f32_16x16x32_bf16 v[128:131], v[96:99], v[178:181], 0
	v_mfma_f32_16x16x32_bf16 v[120:123], v[154:157], v[178:181], 0
	v_mfma_f32_16x16x32_bf16 v[112:115], v[96:99], v[202:205], 0
	v_mfma_f32_16x16x32_bf16 v[104:107], v[154:157], v[202:205], 0
	v_mfma_f32_16x16x32_bf16 v[92:95], v[96:99], v[210:213], 0
	v_mfma_f32_16x16x32_bf16 v[84:87], v[154:157], v[210:213], 0
	v_mfma_f32_16x16x32_bf16 v[76:79], v[96:99], v[218:221], 0
	v_mfma_f32_16x16x32_bf16 v[68:71], v[154:157], v[218:221], 0
	v_mfma_f32_16x16x32_bf16 v[128:131], v[150:153], v[182:185], v[128:131]
	v_mfma_f32_16x16x32_bf16 v[120:123], v[158:161], v[182:185], v[120:123]
	v_mfma_f32_16x16x32_bf16 v[112:115], v[150:153], v[206:209], v[112:115]
	v_mfma_f32_16x16x32_bf16 v[104:107], v[158:161], v[206:209], v[104:107]
	v_mfma_f32_16x16x32_bf16 v[92:95], v[150:153], v[214:217], v[92:95]
	v_mfma_f32_16x16x32_bf16 v[84:87], v[158:161], v[214:217], v[84:87]
	v_mfma_f32_16x16x32_bf16 v[76:79], v[150:153], v[222:225], v[76:79]
	v_mfma_f32_16x16x32_bf16 v[68:71], v[158:161], v[222:225], v[68:71]
	s_setprio 0
	s_setprio 1
	v_mfma_f32_16x16x32_bf16 v[124:127], v[162:165], v[178:181], 0
	v_mfma_f32_16x16x32_bf16 v[116:119], v[170:173], v[178:181], 0
	v_mfma_f32_16x16x32_bf16 v[108:111], v[162:165], v[202:205], 0
	v_mfma_f32_16x16x32_bf16 v[100:103], v[170:173], v[202:205], 0
	v_mfma_f32_16x16x32_bf16 v[88:91], v[162:165], v[210:213], 0
	v_mfma_f32_16x16x32_bf16 v[80:83], v[170:173], v[210:213], 0
	v_mfma_f32_16x16x32_bf16 v[72:75], v[162:165], v[218:221], 0
	v_mfma_f32_16x16x32_bf16 v[64:67], v[170:173], v[218:221], 0
	v_mfma_f32_16x16x32_bf16 v[124:127], v[166:169], v[182:185], v[124:127]
	v_mfma_f32_16x16x32_bf16 v[116:119], v[174:177], v[182:185], v[116:119]
	v_mfma_f32_16x16x32_bf16 v[108:111], v[166:169], v[206:209], v[108:111]
	v_mfma_f32_16x16x32_bf16 v[100:103], v[174:177], v[206:209], v[100:103]
	v_mfma_f32_16x16x32_bf16 v[88:91], v[166:169], v[214:217], v[88:91]
	v_mfma_f32_16x16x32_bf16 v[80:83], v[174:177], v[214:217], v[80:83]
	v_mfma_f32_16x16x32_bf16 v[72:75], v[166:169], v[222:225], v[72:75]
	v_mfma_f32_16x16x32_bf16 v[64:67], v[174:177], v[222:225], v[64:67]
	s_setprio 0
	s_barrier
	s_add_i32 s30, s86, s56
	v_lshl_add_u64 v[186:187], s[36:37], 0, v[188:189]
	s_mov_b32 m0, s30
	ds_read_b128 v[178:181], v149 offset:16384
	ds_read_b128 v[182:185], v149 offset:17408
	ds_read_b128 v[202:205], v149 offset:18432
	ds_read_b128 v[206:209], v149 offset:19456
	ds_read_b128 v[210:213], v149 offset:20480
	ds_read_b128 v[214:217], v149 offset:21504
	ds_read_b128 v[218:221], v149 offset:22528
	ds_read_b128 v[222:225], v149 offset:23552
	global_load_lds_dwordx4 v[186:187], off
	s_add_i32 m0, s30, 0x2000
	s_add_u32 s30, s36, 0x40000
	v_lshl_add_u64 v[226:227], s[36:37], 0, v[132:133]
	s_addc_u32 s31, s37, 0
	s_add_i32 s76, s76, s56
	global_load_lds_dwordx4 v[226:227], off
	v_lshl_add_u64 v[234:235], s[30:31], 0, v[188:189]
	s_mov_b32 m0, s76
	v_lshl_add_u64 v[236:237], s[38:39], 0, v[134:135]
	global_load_lds_dwordx4 v[234:235], off
	v_lshl_add_u64 v[234:235], s[30:31], 0, v[132:133]
	s_add_i32 m0, s76, 0x2000
	s_nop 0
	global_load_lds_dwordx4 v[234:235], off
	v_lshl_add_u64 v[234:235], s[38:39], 0, v[136:137]
	s_mov_b32 m0, s60
	s_nop 0
	global_load_lds_dwordx4 v[234:235], off
	s_mov_b32 m0, s71
	s_nop 0
	global_load_lds_dwordx4 v[236:237], off
	s_waitcnt vmcnt(8)
	s_waitcnt lgkmcnt(0)
	s_barrier
	s_setprio 1
	s_waitcnt lgkmcnt(0)
	v_mfma_f32_16x16x32_bf16 v[60:63], v[96:99], v[178:181], 0
	v_mfma_f32_16x16x32_bf16 v[52:55], v[154:157], v[178:181], 0
	v_mfma_f32_16x16x32_bf16 v[44:47], v[96:99], v[202:205], 0
	v_mfma_f32_16x16x32_bf16 v[36:39], v[154:157], v[202:205], 0
	v_mfma_f32_16x16x32_bf16 v[28:31], v[96:99], v[210:213], 0
	v_mfma_f32_16x16x32_bf16 v[20:23], v[154:157], v[210:213], 0
	v_mfma_f32_16x16x32_bf16 v[12:15], v[96:99], v[218:221], 0
	v_mfma_f32_16x16x32_bf16 v[4:7], v[154:157], v[218:221], 0
	v_mfma_f32_16x16x32_bf16 v[60:63], v[150:153], v[182:185], v[60:63]
	v_mfma_f32_16x16x32_bf16 v[52:55], v[158:161], v[182:185], v[52:55]
	v_mfma_f32_16x16x32_bf16 v[44:47], v[150:153], v[206:209], v[44:47]
	v_mfma_f32_16x16x32_bf16 v[36:39], v[158:161], v[206:209], v[36:39]
	v_mfma_f32_16x16x32_bf16 v[28:31], v[150:153], v[214:217], v[28:31]
	v_mfma_f32_16x16x32_bf16 v[20:23], v[158:161], v[214:217], v[20:23]
	v_mfma_f32_16x16x32_bf16 v[12:15], v[150:153], v[222:225], v[12:15]
	v_mfma_f32_16x16x32_bf16 v[4:7], v[158:161], v[222:225], v[4:7]
	s_setprio 0
	s_setprio 1
	v_mfma_f32_16x16x32_bf16 v[56:59], v[162:165], v[178:181], 0
	v_mfma_f32_16x16x32_bf16 v[48:51], v[170:173], v[178:181], 0
	v_mfma_f32_16x16x32_bf16 v[40:43], v[162:165], v[202:205], 0
	v_mfma_f32_16x16x32_bf16 v[32:35], v[170:173], v[202:205], 0
	v_mfma_f32_16x16x32_bf16 v[24:27], v[162:165], v[210:213], 0
	v_mfma_f32_16x16x32_bf16 v[16:19], v[170:173], v[210:213], 0
	v_mfma_f32_16x16x32_bf16 v[8:11], v[162:165], v[218:221], 0
	v_mfma_f32_16x16x32_bf16 v[0:3], v[170:173], v[218:221], 0
	v_mfma_f32_16x16x32_bf16 v[56:59], v[166:169], v[182:185], v[56:59]
	v_mfma_f32_16x16x32_bf16 v[48:51], v[174:177], v[182:185], v[48:51]
	v_mfma_f32_16x16x32_bf16 v[40:43], v[166:169], v[206:209], v[40:43]
	v_mfma_f32_16x16x32_bf16 v[32:35], v[174:177], v[206:209], v[32:35]
	v_mfma_f32_16x16x32_bf16 v[24:27], v[166:169], v[214:217], v[24:27]
	v_mfma_f32_16x16x32_bf16 v[16:19], v[174:177], v[214:217], v[16:19]
	v_mfma_f32_16x16x32_bf16 v[8:11], v[166:169], v[222:225], v[8:11]
	v_mfma_f32_16x16x32_bf16 v[0:3], v[174:177], v[222:225], v[0:3]
	s_setprio 0
	s_barrier
	s_add_i32 s76, 0, 0x18000
	v_add_u32_e32 v138, s76, v141
	s_add_i32 s77, 0, 0x1c000
	ds_read_b128 v[96:99], v138
	ds_read_b128 v[150:153], v138 offset:1024
	ds_read_b128 v[154:157], v138 offset:2048
	ds_read_b128 v[158:161], v138 offset:3072
	v_add_u32_e32 v138, s77, v141
	ds_read_b128 v[162:165], v138
	ds_read_b128 v[166:169], v138 offset:1024
	ds_read_b128 v[170:173], v138 offset:2048
	ds_read_b128 v[174:177], v138 offset:3072
	s_add_u32 s30, s38, 0x40000
	s_addc_u32 s31, s39, 0
	s_mov_b32 m0, s87
	v_lshl_add_u64 v[238:239], s[30:31], 0, v[136:137]
	ds_read_b128 v[178:181], v149 offset:32768
	ds_read_b128 v[182:185], v149 offset:33792
	ds_read_b128 v[202:205], v149 offset:34816
	ds_read_b128 v[206:209], v149 offset:35840
	ds_read_b128 v[210:213], v149 offset:36864
	ds_read_b128 v[214:217], v149 offset:37888
	ds_read_b128 v[218:221], v149 offset:38912
	ds_read_b128 v[222:225], v149 offset:39936
	global_load_lds_dwordx4 v[238:239], off
	v_lshl_add_u64 v[238:239], s[30:31], 0, v[134:135]
	s_mov_b32 m0, s89
	s_nop 0
	global_load_lds_dwordx4 v[238:239], off
	s_waitcnt vmcnt(8)
	s_waitcnt lgkmcnt(0)
	s_barrier
	s_setprio 1
	s_waitcnt lgkmcnt(0)
	v_mfma_f32_16x16x32_bf16 v[128:131], v[96:99], v[178:181], v[128:131]
	v_mfma_f32_16x16x32_bf16 v[120:123], v[154:157], v[178:181], v[120:123]
	v_mfma_f32_16x16x32_bf16 v[112:115], v[96:99], v[202:205], v[112:115]
	v_mfma_f32_16x16x32_bf16 v[104:107], v[154:157], v[202:205], v[104:107]
	v_mfma_f32_16x16x32_bf16 v[92:95], v[96:99], v[210:213], v[92:95]
	v_mfma_f32_16x16x32_bf16 v[84:87], v[154:157], v[210:213], v[84:87]
	v_mfma_f32_16x16x32_bf16 v[76:79], v[96:99], v[218:221], v[76:79]
	v_mfma_f32_16x16x32_bf16 v[68:71], v[154:157], v[218:221], v[68:71]
	v_mfma_f32_16x16x32_bf16 v[128:131], v[150:153], v[182:185], v[128:131]
	v_mfma_f32_16x16x32_bf16 v[120:123], v[158:161], v[182:185], v[120:123]
	v_mfma_f32_16x16x32_bf16 v[112:115], v[150:153], v[206:209], v[112:115]
	v_mfma_f32_16x16x32_bf16 v[104:107], v[158:161], v[206:209], v[104:107]
	v_mfma_f32_16x16x32_bf16 v[92:95], v[150:153], v[214:217], v[92:95]
	v_mfma_f32_16x16x32_bf16 v[84:87], v[158:161], v[214:217], v[84:87]
	v_mfma_f32_16x16x32_bf16 v[76:79], v[150:153], v[222:225], v[76:79]
	v_mfma_f32_16x16x32_bf16 v[68:71], v[158:161], v[222:225], v[68:71]
	s_setprio 0
	s_setprio 1
	v_mfma_f32_16x16x32_bf16 v[124:127], v[162:165], v[178:181], v[124:127]
	v_mfma_f32_16x16x32_bf16 v[116:119], v[170:173], v[178:181], v[116:119]
	v_mfma_f32_16x16x32_bf16 v[108:111], v[162:165], v[202:205], v[108:111]
	v_mfma_f32_16x16x32_bf16 v[100:103], v[170:173], v[202:205], v[100:103]
	v_mfma_f32_16x16x32_bf16 v[88:91], v[162:165], v[210:213], v[88:91]
	v_mfma_f32_16x16x32_bf16 v[80:83], v[170:173], v[210:213], v[80:83]
	v_mfma_f32_16x16x32_bf16 v[72:75], v[162:165], v[218:221], v[72:75]
	v_mfma_f32_16x16x32_bf16 v[64:67], v[170:173], v[218:221], v[64:67]
	v_mfma_f32_16x16x32_bf16 v[124:127], v[166:169], v[182:185], v[124:127]
	v_mfma_f32_16x16x32_bf16 v[116:119], v[174:177], v[182:185], v[116:119]
	v_mfma_f32_16x16x32_bf16 v[108:111], v[166:169], v[206:209], v[108:111]
	v_mfma_f32_16x16x32_bf16 v[100:103], v[174:177], v[206:209], v[100:103]
	v_mfma_f32_16x16x32_bf16 v[88:91], v[166:169], v[214:217], v[88:91]
	v_mfma_f32_16x16x32_bf16 v[80:83], v[174:177], v[214:217], v[80:83]
	v_mfma_f32_16x16x32_bf16 v[72:75], v[166:169], v[222:225], v[72:75]
	v_mfma_f32_16x16x32_bf16 v[64:67], v[174:177], v[222:225], v[64:67]
	s_setprio 0
	s_barrier
	s_add_i32 s30, s76, s56
	v_lshl_add_u64 v[186:187], v[186:187], 0, s[72:73]
	s_mov_b32 m0, s30
	ds_read_b128 v[178:181], v149 offset:49152
	ds_read_b128 v[182:185], v149 offset:50176
	ds_read_b128 v[202:205], v149 offset:51200
	ds_read_b128 v[206:209], v149 offset:52224
	ds_read_b128 v[210:213], v149 offset:53248
	ds_read_b128 v[214:217], v149 offset:54272
	ds_read_b128 v[218:221], v149 offset:55296
	ds_read_b128 v[222:225], v149 offset:56320
	global_load_lds_dwordx4 v[186:187], off
	s_add_i32 m0, s30, 0x2000
	s_add_u32 s30, s36, 0x40080
	v_lshl_add_u64 v[186:187], v[226:227], 0, s[72:73]
	s_addc_u32 s31, s37, 0
	s_add_i32 s36, s77, s56
	global_load_lds_dwordx4 v[186:187], off
	v_lshl_add_u64 v[186:187], s[30:31], 0, v[188:189]
	s_mov_b32 m0, s36
	s_nop 0
	global_load_lds_dwordx4 v[186:187], off
	v_lshl_add_u64 v[186:187], s[30:31], 0, v[132:133]
	s_add_i32 m0, s36, 0x2000
	s_nop 0
	global_load_lds_dwordx4 v[186:187], off
	v_lshl_add_u64 v[186:187], v[234:235], 0, s[72:73]
	s_mov_b32 m0, s90
	s_nop 0
	global_load_lds_dwordx4 v[186:187], off
	v_lshl_add_u64 v[186:187], v[236:237], 0, s[72:73]
	s_mov_b32 m0, s91
	s_nop 0
	global_load_lds_dwordx4 v[186:187], off
	s_waitcnt vmcnt(8)
	s_waitcnt lgkmcnt(0)
	s_barrier
	s_setprio 1
	s_waitcnt lgkmcnt(0)
	v_mfma_f32_16x16x32_bf16 v[60:63], v[96:99], v[178:181], v[60:63]
	v_mfma_f32_16x16x32_bf16 v[52:55], v[154:157], v[178:181], v[52:55]
	v_mfma_f32_16x16x32_bf16 v[44:47], v[96:99], v[202:205], v[44:47]
	v_mfma_f32_16x16x32_bf16 v[36:39], v[154:157], v[202:205], v[36:39]
	v_mfma_f32_16x16x32_bf16 v[28:31], v[96:99], v[210:213], v[28:31]
	v_mfma_f32_16x16x32_bf16 v[20:23], v[154:157], v[210:213], v[20:23]
	v_mfma_f32_16x16x32_bf16 v[12:15], v[96:99], v[218:221], v[12:15]
	v_mfma_f32_16x16x32_bf16 v[4:7], v[154:157], v[218:221], v[4:7]
	v_mfma_f32_16x16x32_bf16 v[60:63], v[150:153], v[182:185], v[60:63]
	v_mfma_f32_16x16x32_bf16 v[52:55], v[158:161], v[182:185], v[52:55]
	v_mfma_f32_16x16x32_bf16 v[44:47], v[150:153], v[206:209], v[44:47]
	v_mfma_f32_16x16x32_bf16 v[36:39], v[158:161], v[206:209], v[36:39]
	v_mfma_f32_16x16x32_bf16 v[28:31], v[150:153], v[214:217], v[28:31]
	v_mfma_f32_16x16x32_bf16 v[20:23], v[158:161], v[214:217], v[20:23]
	v_mfma_f32_16x16x32_bf16 v[12:15], v[150:153], v[222:225], v[12:15]
	v_mfma_f32_16x16x32_bf16 v[4:7], v[158:161], v[222:225], v[4:7]
	s_setprio 0
	s_setprio 1
	v_mfma_f32_16x16x32_bf16 v[56:59], v[162:165], v[178:181], v[56:59]
	v_mfma_f32_16x16x32_bf16 v[48:51], v[170:173], v[178:181], v[48:51]
	v_mfma_f32_16x16x32_bf16 v[40:43], v[162:165], v[202:205], v[40:43]
	v_mfma_f32_16x16x32_bf16 v[32:35], v[170:173], v[202:205], v[32:35]
	v_mfma_f32_16x16x32_bf16 v[24:27], v[162:165], v[210:213], v[24:27]
	v_mfma_f32_16x16x32_bf16 v[16:19], v[170:173], v[210:213], v[16:19]
	v_mfma_f32_16x16x32_bf16 v[8:11], v[162:165], v[218:221], v[8:11]
	v_mfma_f32_16x16x32_bf16 v[0:3], v[170:173], v[218:221], v[0:3]
	v_mfma_f32_16x16x32_bf16 v[56:59], v[166:169], v[182:185], v[56:59]
	v_mfma_f32_16x16x32_bf16 v[48:51], v[174:177], v[182:185], v[48:51]
	v_mfma_f32_16x16x32_bf16 v[40:43], v[166:169], v[206:209], v[40:43]
	v_mfma_f32_16x16x32_bf16 v[32:35], v[174:177], v[206:209], v[32:35]
	v_mfma_f32_16x16x32_bf16 v[24:27], v[166:169], v[214:217], v[24:27]
	v_mfma_f32_16x16x32_bf16 v[16:19], v[174:177], v[214:217], v[16:19]
	v_mfma_f32_16x16x32_bf16 v[8:11], v[166:169], v[222:225], v[8:11]
	v_mfma_f32_16x16x32_bf16 v[0:3], v[174:177], v[222:225], v[0:3]
	s_setprio 0
	s_barrier
	s_add_i32 s43, s43, 2
	s_cmp_gt_u32 s43, 13
	s_mov_b64 s[30:31], s[34:35]
	s_cbranch_scc1 .Lpeel_exit_swiglu

.Lpeel_exit_swiglu:
	s_and_b64 vcc, exec, s[14:15]
	s_cbranch_vccz .LBB0_531
	s_barrier
.LBB0_531:
	v_lshl_add_u32 v154, s54, 12, v145
	ds_read_b128 v[96:99], v154
	s_waitcnt lgkmcnt(0)
	v_mov_b32_e32 v150, v97
	v_mov_b32_e32 v151, v98
	v_mov_b32_e32 v97, v99
	v_pk_add_f32 v[96:97], v[150:151], v[96:97]
	v_lshl_add_u32 v151, s24, 8, v139
	v_add_f32_e32 v96, v96, v97
	v_fmamk_f32 v96, v96, 0x3a800000, v229
	v_rsq_f32_e32 v150, v96
	ds_read_b128 v[96:99], v154 offset:256
	v_pk_mul_f32 v[128:129], v[128:129], v[150:151] op_sel_hi:[1,0]
	v_pk_mul_f32 v[124:125], v[124:125], v[150:151] op_sel_hi:[1,0]
	s_waitcnt lgkmcnt(0)
	v_mov_b32_e32 v152, v97
	v_mov_b32_e32 v153, v98
	v_mov_b32_e32 v97, v99
	v_pk_add_f32 v[96:97], v[152:153], v[96:97]
	v_pk_mul_f32 v[124:125], v[124:125], v[128:129]
	v_add_f32_e32 v96, v96, v97
	v_fmamk_f32 v96, v96, 0x3a800000, v229
	v_rsq_f32_e32 v148, v96
	ds_read_b128 v[96:99], v154 offset:512
	v_pk_mul_f32 v[128:129], v[128:129], s[68:69] op_sel_hi:[1,0]
	v_pk_mul_f32 v[126:127], v[126:127], v[150:151] op_sel_hi:[1,0]
	v_exp_f32_e32 v128, v128
	v_exp_f32_e32 v129, v129
	s_waitcnt lgkmcnt(0)
	v_mov_b32_e32 v152, v97
	v_mov_b32_e32 v153, v98
	v_mov_b32_e32 v97, v99
	v_pk_add_f32 v[96:97], v[152:153], v[96:97]
	v_pk_add_f32 v[128:129], v[128:129], 1.0 op_sel_hi:[1,0]
	v_add_f32_e32 v96, v96, v97
	v_fmamk_f32 v96, v96, 0x3a800000, v229
	v_rsq_f32_e32 v146, v96
	ds_read_b128 v[96:99], v154 offset:768
	v_rcp_f32_e32 v128, v128
	v_rcp_f32_e32 v129, v129
	v_pk_mul_f32 v[120:121], v[120:121], v[150:151] op_sel_hi:[1,0]
	v_pk_mul_f32 v[116:117], v[116:117], v[150:151] op_sel_hi:[1,0]
	s_waitcnt lgkmcnt(0)
	v_mov_b32_e32 v152, v97
	v_mov_b32_e32 v153, v98
	v_mov_b32_e32 v97, v99
	v_pk_add_f32 v[96:97], v[152:153], v[96:97]
	v_pk_mul_f32 v[124:125], v[124:125], v[128:129]
	v_add_f32_e32 v96, v96, v97
	v_fmamk_f32 v96, v96, 0x3a800000, v229
	v_rsq_f32_e32 v144, v96
	ds_read_b128 v[96:99], v154 offset:2048
	v_pk_mul_f32 v[128:129], v[130:131], v[150:151] op_sel_hi:[1,0]
	v_pk_mul_f32 v[116:117], v[120:121], v[116:117]
	v_pk_mul_f32 v[126:127], v[128:129], v[126:127]
	v_pk_mul_f32 v[128:129], v[128:129], s[68:69] op_sel_hi:[1,0]
	s_waitcnt lgkmcnt(0)
	v_mov_b32_e32 v152, v97
	v_mov_b32_e32 v153, v98
	v_mov_b32_e32 v97, v99
	v_pk_add_f32 v[96:97], v[152:153], v[96:97]
	v_pk_mul_f32 v[120:121], v[120:121], s[68:69] op_sel_hi:[1,0]
	v_add_f32_e32 v96, v96, v97
	v_fmamk_f32 v96, v96, 0x3a800000, v229
	v_rsq_f32_e32 v142, v96
	ds_read_b128 v[96:99], v154 offset:2304
	v_exp_f32_e32 v128, v128
	v_exp_f32_e32 v129, v129
	v_exp_f32_e32 v120, v120
	v_exp_f32_e32 v121, v121
	s_waitcnt lgkmcnt(0)
	v_mov_b32_e32 v152, v97
	v_mov_b32_e32 v153, v98
	v_mov_b32_e32 v97, v99
	v_pk_add_f32 v[96:97], v[152:153], v[96:97]
	v_pk_mul_f32 v[112:113], v[112:113], v[148:149] op_sel_hi:[1,0]
	v_add_f32_e32 v96, v96, v97
	v_fmamk_f32 v96, v96, 0x3a800000, v229
	v_rsq_f32_e32 v140, v96
	ds_read_b128 v[96:99], v154 offset:2560
	v_pk_mul_f32 v[108:109], v[108:109], v[148:149] op_sel_hi:[1,0]
	v_pk_add_f32 v[128:129], v[128:129], 1.0 op_sel_hi:[1,0]
	v_pk_mul_f32 v[108:109], v[108:109], v[112:113]
	v_pk_mul_f32 v[112:113], v[112:113], s[68:69] op_sel_hi:[1,0]
	v_pk_add_f32 v[120:121], v[120:121], 1.0 op_sel_hi:[1,0]
	v_exp_f32_e32 v112, v112
	v_exp_f32_e32 v113, v113
	v_rcp_f32_e32 v128, v128
	v_rcp_f32_e32 v129, v129
	v_rcp_f32_e32 v120, v120
	v_rcp_f32_e32 v121, v121
	s_waitcnt lgkmcnt(0)
	v_mov_b32_e32 v152, v97
	v_mov_b32_e32 v153, v98
	v_mov_b32_e32 v97, v99
	v_pk_add_f32 v[96:97], v[152:153], v[96:97]
	v_pk_add_f32 v[112:113], v[112:113], 1.0 op_sel_hi:[1,0]
	v_add_f32_e32 v96, v96, v97
	v_fmamk_f32 v96, v96, 0x3a800000, v229
	v_pk_mul_f32 v[126:127], v[126:127], v[128:129]
	v_pk_mul_f32 v[116:117], v[116:117], v[120:121]
	v_rcp_f32_e32 v112, v112
	v_rcp_f32_e32 v113, v113
	v_rsq_f32_e32 v138, v96
	ds_read_b128 v[96:99], v154 offset:2816
	v_cvt_pk_bf16_f32 v124, v124, v125
	v_cvt_pk_bf16_f32 v125, v126, v127
	v_cvt_pk_bf16_f32 v126, v116, v117
	v_pk_mul_f32 v[116:117], v[122:123], v[150:151] op_sel_hi:[1,0]
	v_pk_mul_f32 v[118:119], v[118:119], v[150:151] op_sel_hi:[1,0]
	v_pk_mul_f32 v[108:109], v[108:109], v[112:113]
	v_pk_mul_f32 v[118:119], v[116:117], v[118:119]
	v_pk_mul_f32 v[116:117], v[116:117], s[68:69] op_sel_hi:[1,0]
	v_pk_mul_f32 v[112:113], v[114:115], v[148:149] op_sel_hi:[1,0]
	v_exp_f32_e32 v116, v116
	v_exp_f32_e32 v117, v117
	v_pk_mul_f32 v[110:111], v[110:111], v[148:149] op_sel_hi:[1,0]
	v_pk_mul_f32 v[104:105], v[104:105], v[148:149] op_sel_hi:[1,0]
	v_pk_mul_f32 v[100:101], v[100:101], v[148:149] op_sel_hi:[1,0]
	v_pk_mul_f32 v[110:111], v[112:113], v[110:111]
	v_pk_mul_f32 v[112:113], v[112:113], s[68:69] op_sel_hi:[1,0]
	v_pk_mul_f32 v[100:101], v[104:105], v[100:101]
	v_pk_mul_f32 v[104:105], v[104:105], s[68:69] op_sel_hi:[1,0]
	v_exp_f32_e32 v112, v112
	v_exp_f32_e32 v113, v113
	v_exp_f32_e32 v104, v104
	v_exp_f32_e32 v105, v105
	v_pk_add_f32 v[116:117], v[116:117], 1.0 op_sel_hi:[1,0]
	v_pk_mul_f32 v[92:93], v[92:93], v[146:147] op_sel_hi:[1,0]
	v_rcp_f32_e32 v116, v116
	v_rcp_f32_e32 v117, v117
	v_pk_mul_f32 v[88:89], v[88:89], v[146:147] op_sel_hi:[1,0]
	v_pk_add_f32 v[112:113], v[112:113], 1.0 op_sel_hi:[1,0]
	v_pk_mul_f32 v[88:89], v[88:89], v[92:93]
	v_pk_mul_f32 v[92:93], v[92:93], s[68:69] op_sel_hi:[1,0]
	v_pk_add_f32 v[104:105], v[104:105], 1.0 op_sel_hi:[1,0]
	v_exp_f32_e32 v92, v92
	v_exp_f32_e32 v93, v93
	v_rcp_f32_e32 v112, v112
	v_rcp_f32_e32 v113, v113
	v_rcp_f32_e32 v104, v104
	v_rcp_f32_e32 v105, v105
	v_lshl_or_b32 v152, s1, 7, v147
	v_pk_mul_f32 v[116:117], v[118:119], v[116:117]
	v_ashrrev_i32_e32 v153, 31, v152
	v_cvt_pk_bf16_f32 v127, v116, v117
	v_mov_b64_e32 v[116:117], s[8:9]
	v_mad_i64_i32 v[120:121], s[0:1], v151, s42, v[116:117]
	v_lshlrev_b64 v[118:119], 1, v[152:153]
	v_pk_add_f32 v[92:93], v[92:93], 1.0 op_sel_hi:[1,0]
	v_lshl_add_u64 v[120:121], v[120:121], 0, v[118:119]
	v_pk_mul_f32 v[110:111], v[110:111], v[112:113]
	v_pk_mul_f32 v[100:101], v[100:101], v[104:105]
	v_rcp_f32_e32 v92, v92
	v_rcp_f32_e32 v93, v93
	global_store_dwordx4 v[120:121], v[124:127], off
	v_cvt_pk_bf16_f32 v108, v108, v109
	v_cvt_pk_bf16_f32 v109, v110, v111
	v_cvt_pk_bf16_f32 v110, v100, v101
	v_pk_mul_f32 v[100:101], v[106:107], v[148:149] op_sel_hi:[1,0]
	v_pk_mul_f32 v[102:103], v[102:103], v[148:149] op_sel_hi:[1,0]
	v_pk_mul_f32 v[88:89], v[88:89], v[92:93]
	v_pk_mul_f32 v[102:103], v[100:101], v[102:103]
	v_pk_mul_f32 v[100:101], v[100:101], s[68:69] op_sel_hi:[1,0]
	v_pk_mul_f32 v[92:93], v[94:95], v[146:147] op_sel_hi:[1,0]
	v_exp_f32_e32 v100, v100
	v_exp_f32_e32 v101, v101
	v_pk_mul_f32 v[90:91], v[90:91], v[146:147] op_sel_hi:[1,0]
	v_pk_mul_f32 v[84:85], v[84:85], v[146:147] op_sel_hi:[1,0]
	v_pk_mul_f32 v[80:81], v[80:81], v[146:147] op_sel_hi:[1,0]
	v_pk_mul_f32 v[90:91], v[92:93], v[90:91]
	v_pk_mul_f32 v[92:93], v[92:93], s[68:69] op_sel_hi:[1,0]
	v_pk_mul_f32 v[80:81], v[84:85], v[80:81]
	v_pk_mul_f32 v[84:85], v[84:85], s[68:69] op_sel_hi:[1,0]
	v_exp_f32_e32 v92, v92
	v_exp_f32_e32 v93, v93
	v_exp_f32_e32 v84, v84
	v_exp_f32_e32 v85, v85
	v_pk_add_f32 v[100:101], v[100:101], 1.0 op_sel_hi:[1,0]
	v_pk_mul_f32 v[76:77], v[76:77], v[144:145] op_sel_hi:[1,0]
	v_rcp_f32_e32 v100, v100
	v_rcp_f32_e32 v101, v101
	v_pk_mul_f32 v[72:73], v[72:73], v[144:145] op_sel_hi:[1,0]
	v_pk_add_f32 v[92:93], v[92:93], 1.0 op_sel_hi:[1,0]
	v_pk_mul_f32 v[72:73], v[72:73], v[76:77]
	v_pk_mul_f32 v[76:77], v[76:77], s[68:69] op_sel_hi:[1,0]
	v_pk_add_f32 v[84:85], v[84:85], 1.0 op_sel_hi:[1,0]
	v_exp_f32_e32 v76, v76
	v_exp_f32_e32 v77, v77
	v_rcp_f32_e32 v92, v92
	v_rcp_f32_e32 v93, v93
	v_rcp_f32_e32 v84, v84
	v_rcp_f32_e32 v85, v85
	v_pk_mul_f32 v[100:101], v[102:103], v[100:101]
	v_pk_add_f32 v[76:77], v[76:77], 1.0 op_sel_hi:[1,0]
	v_cvt_pk_bf16_f32 v111, v100, v101
	v_or_b32_e32 v100, 16, v151
	v_mad_i64_i32 v[100:101], s[0:1], v100, s42, v[116:117]
	v_lshl_add_u64 v[100:101], v[100:101], 0, v[118:119]
	v_pk_mul_f32 v[90:91], v[90:91], v[92:93]
	v_pk_mul_f32 v[80:81], v[80:81], v[84:85]
	v_rcp_f32_e32 v76, v76
	v_rcp_f32_e32 v77, v77
	global_store_dwordx4 v[100:101], v[108:111], off
	v_cvt_pk_bf16_f32 v88, v88, v89
	v_cvt_pk_bf16_f32 v89, v90, v91
	v_cvt_pk_bf16_f32 v90, v80, v81
	v_pk_mul_f32 v[80:81], v[86:87], v[146:147] op_sel_hi:[1,0]
	v_pk_mul_f32 v[82:83], v[82:83], v[146:147] op_sel_hi:[1,0]
	v_pk_mul_f32 v[72:73], v[72:73], v[76:77]
	v_pk_mul_f32 v[82:83], v[80:81], v[82:83]
	v_pk_mul_f32 v[80:81], v[80:81], s[68:69] op_sel_hi:[1,0]
	v_pk_mul_f32 v[76:77], v[78:79], v[144:145] op_sel_hi:[1,0]
	v_exp_f32_e32 v80, v80
	v_exp_f32_e32 v81, v81
	v_pk_mul_f32 v[74:75], v[74:75], v[144:145] op_sel_hi:[1,0]
	v_pk_mul_f32 v[68:69], v[68:69], v[144:145] op_sel_hi:[1,0]
	v_pk_mul_f32 v[64:65], v[64:65], v[144:145] op_sel_hi:[1,0]
	v_pk_mul_f32 v[74:75], v[76:77], v[74:75]
	v_pk_mul_f32 v[76:77], v[76:77], s[68:69] op_sel_hi:[1,0]
	v_pk_mul_f32 v[64:65], v[68:69], v[64:65]
	v_pk_mul_f32 v[68:69], v[68:69], s[68:69] op_sel_hi:[1,0]
	v_exp_f32_e32 v76, v76
	v_exp_f32_e32 v77, v77
	v_exp_f32_e32 v68, v68
	v_exp_f32_e32 v69, v69
	v_pk_add_f32 v[80:81], v[80:81], 1.0 op_sel_hi:[1,0]
	v_pk_add_f32 v[76:77], v[76:77], 1.0 op_sel_hi:[1,0]
	v_rcp_f32_e32 v80, v80
	v_rcp_f32_e32 v81, v81
	v_pk_add_f32 v[68:69], v[68:69], 1.0 op_sel_hi:[1,0]
	v_rcp_f32_e32 v76, v76
	v_rcp_f32_e32 v77, v77
	v_rcp_f32_e32 v68, v68
	v_rcp_f32_e32 v69, v69
	v_pk_mul_f32 v[80:81], v[82:83], v[80:81]
	v_pk_mul_f32 v[74:75], v[74:75], v[76:77]
	v_cvt_pk_bf16_f32 v91, v80, v81
	v_or_b32_e32 v80, 32, v151
	v_mad_i64_i32 v[80:81], s[0:1], v80, s42, v[116:117]
	v_lshl_add_u64 v[80:81], v[80:81], 0, v[118:119]
	v_pk_mul_f32 v[64:65], v[64:65], v[68:69]
	global_store_dwordx4 v[80:81], v[88:91], off
	v_cvt_pk_bf16_f32 v72, v72, v73
	v_cvt_pk_bf16_f32 v73, v74, v75
	v_cvt_pk_bf16_f32 v74, v64, v65
	v_pk_mul_f32 v[64:65], v[70:71], v[144:145] op_sel_hi:[1,0]
	v_pk_mul_f32 v[66:67], v[66:67], v[144:145] op_sel_hi:[1,0]
	s_nop 0
	v_pk_mul_f32 v[66:67], v[64:65], v[66:67]
	v_pk_mul_f32 v[64:65], v[64:65], s[68:69] op_sel_hi:[1,0]
	s_nop 0
	v_exp_f32_e32 v64, v64
	v_exp_f32_e32 v65, v65
	s_nop 0
	v_pk_add_f32 v[64:65], v[64:65], 1.0 op_sel_hi:[1,0]
	s_nop 0
	v_rcp_f32_e32 v64, v64
	v_rcp_f32_e32 v65, v65
	s_nop 0
	v_pk_mul_f32 v[64:65], v[66:67], v[64:65]
	s_nop 0
	v_cvt_pk_bf16_f32 v75, v64, v65
	v_or_b32_e32 v64, 48, v151
	v_mad_i64_i32 v[64:65], s[0:1], v64, s42, v[116:117]
	v_lshl_add_u64 v[64:65], v[64:65], 0, v[118:119]
	global_store_dwordx4 v[64:65], v[72:75], off
	v_add_u32_e32 v64, 0x80, v151
	v_pk_mul_f32 v[60:61], v[60:61], v[142:143] op_sel_hi:[1,0]
	v_pk_mul_f32 v[56:57], v[56:57], v[142:143] op_sel_hi:[1,0]
	v_pk_mul_f32 v[58:59], v[58:59], v[142:143] op_sel_hi:[1,0]
	v_pk_mul_f32 v[56:57], v[60:61], v[56:57]
	v_pk_mul_f32 v[60:61], v[60:61], s[68:69] op_sel_hi:[1,0]
	v_pk_mul_f32 v[52:53], v[52:53], v[142:143] op_sel_hi:[1,0]
	v_exp_f32_e32 v60, v60
	v_exp_f32_e32 v61, v61
	v_pk_mul_f32 v[48:49], v[48:49], v[142:143] op_sel_hi:[1,0]
	v_pk_mul_f32 v[44:45], v[44:45], v[140:141] op_sel_hi:[1,0]
	v_pk_mul_f32 v[48:49], v[52:53], v[48:49]
	v_pk_add_f32 v[60:61], v[60:61], 1.0 op_sel_hi:[1,0]
	v_pk_mul_f32 v[52:53], v[52:53], s[68:69] op_sel_hi:[1,0]
	v_rcp_f32_e32 v60, v60
	v_rcp_f32_e32 v61, v61
	v_exp_f32_e32 v52, v52
	v_exp_f32_e32 v53, v53
	v_pk_mul_f32 v[40:41], v[40:41], v[140:141] op_sel_hi:[1,0]
	v_pk_mul_f32 v[56:57], v[56:57], v[60:61]
	v_pk_mul_f32 v[60:61], v[62:63], v[142:143] op_sel_hi:[1,0]
	v_pk_mul_f32 v[40:41], v[40:41], v[44:45]
	v_pk_mul_f32 v[58:59], v[60:61], v[58:59]
	v_pk_mul_f32 v[60:61], v[60:61], s[68:69] op_sel_hi:[1,0]
	v_pk_mul_f32 v[44:45], v[44:45], s[68:69] op_sel_hi:[1,0]
	v_exp_f32_e32 v60, v60
	v_exp_f32_e32 v61, v61
	v_exp_f32_e32 v44, v44
	v_exp_f32_e32 v45, v45
	v_pk_add_f32 v[52:53], v[52:53], 1.0 op_sel_hi:[1,0]
	v_pk_add_f32 v[60:61], v[60:61], 1.0 op_sel_hi:[1,0]
	v_rcp_f32_e32 v52, v52
	v_rcp_f32_e32 v60, v60
	v_rcp_f32_e32 v61, v61
	v_rcp_f32_e32 v53, v53
	v_pk_add_f32 v[44:45], v[44:45], 1.0 op_sel_hi:[1,0]
	v_cvt_pk_bf16_f32 v56, v56, v57
	v_pk_mul_f32 v[58:59], v[58:59], v[60:61]
	v_rcp_f32_e32 v44, v44
	v_rcp_f32_e32 v45, v45
	v_pk_mul_f32 v[48:49], v[48:49], v[52:53]
	v_cvt_pk_bf16_f32 v57, v58, v59
	v_pk_mul_f32 v[50:51], v[50:51], v[142:143] op_sel_hi:[1,0]
	v_cvt_pk_bf16_f32 v58, v48, v49
	v_pk_mul_f32 v[48:49], v[54:55], v[142:143] op_sel_hi:[1,0]
	v_pk_mul_f32 v[40:41], v[40:41], v[44:45]
	v_pk_mul_f32 v[50:51], v[48:49], v[50:51]
	v_pk_mul_f32 v[48:49], v[48:49], s[68:69] op_sel_hi:[1,0]
	v_pk_mul_f32 v[44:45], v[46:47], v[140:141] op_sel_hi:[1,0]
	v_exp_f32_e32 v48, v48
	v_exp_f32_e32 v49, v49
	v_pk_mul_f32 v[42:43], v[42:43], v[140:141] op_sel_hi:[1,0]
	v_pk_mul_f32 v[36:37], v[36:37], v[140:141] op_sel_hi:[1,0]
	v_pk_mul_f32 v[32:33], v[32:33], v[140:141] op_sel_hi:[1,0]
	v_pk_mul_f32 v[42:43], v[44:45], v[42:43]
	v_pk_mul_f32 v[44:45], v[44:45], s[68:69] op_sel_hi:[1,0]
	v_pk_mul_f32 v[32:33], v[36:37], v[32:33]
	v_pk_mul_f32 v[36:37], v[36:37], s[68:69] op_sel_hi:[1,0]
	v_exp_f32_e32 v44, v44
	v_exp_f32_e32 v45, v45
	v_exp_f32_e32 v36, v36
	v_exp_f32_e32 v37, v37
	v_pk_add_f32 v[48:49], v[48:49], 1.0 op_sel_hi:[1,0]
	v_pk_mul_f32 v[28:29], v[28:29], v[138:139] op_sel_hi:[1,0]
	v_pk_mul_f32 v[24:25], v[24:25], v[138:139] op_sel_hi:[1,0]
	v_rcp_f32_e32 v48, v48
	v_rcp_f32_e32 v49, v49
	v_pk_mul_f32 v[24:25], v[24:25], v[28:29]
	v_pk_mul_f32 v[28:29], v[28:29], s[68:69] op_sel_hi:[1,0]
	v_pk_add_f32 v[44:45], v[44:45], 1.0 op_sel_hi:[1,0]
	v_pk_add_f32 v[36:37], v[36:37], 1.0 op_sel_hi:[1,0]
	v_exp_f32_e32 v28, v28
	v_exp_f32_e32 v29, v29
	v_rcp_f32_e32 v44, v44
	v_rcp_f32_e32 v45, v45
	v_rcp_f32_e32 v36, v36
	v_rcp_f32_e32 v37, v37
	v_pk_mul_f32 v[48:49], v[50:51], v[48:49]
	v_pk_add_f32 v[28:29], v[28:29], 1.0 op_sel_hi:[1,0]
	v_cvt_pk_bf16_f32 v59, v48, v49
	v_mad_i64_i32 v[48:49], s[0:1], v64, s42, v[116:117]
	v_lshl_add_u64 v[48:49], v[48:49], 0, v[118:119]
	v_pk_mul_f32 v[42:43], v[42:43], v[44:45]
	v_pk_mul_f32 v[32:33], v[32:33], v[36:37]
	v_rcp_f32_e32 v28, v28
	v_rcp_f32_e32 v29, v29
	global_store_dwordx4 v[48:49], v[56:59], off
	v_cvt_pk_bf16_f32 v40, v40, v41
	v_cvt_pk_bf16_f32 v41, v42, v43
	v_cvt_pk_bf16_f32 v42, v32, v33
	v_pk_mul_f32 v[32:33], v[38:39], v[140:141] op_sel_hi:[1,0]
	v_pk_mul_f32 v[34:35], v[34:35], v[140:141] op_sel_hi:[1,0]
	v_pk_mul_f32 v[24:25], v[24:25], v[28:29]
	v_pk_mul_f32 v[34:35], v[32:33], v[34:35]
	v_pk_mul_f32 v[32:33], v[32:33], s[68:69] op_sel_hi:[1,0]
	v_pk_mul_f32 v[28:29], v[30:31], v[138:139] op_sel_hi:[1,0]
	v_exp_f32_e32 v32, v32
	v_exp_f32_e32 v33, v33
	v_pk_mul_f32 v[26:27], v[26:27], v[138:139] op_sel_hi:[1,0]
	v_pk_mul_f32 v[20:21], v[20:21], v[138:139] op_sel_hi:[1,0]
	v_pk_mul_f32 v[16:17], v[16:17], v[138:139] op_sel_hi:[1,0]
	v_pk_mul_f32 v[26:27], v[28:29], v[26:27]
	v_pk_mul_f32 v[28:29], v[28:29], s[68:69] op_sel_hi:[1,0]
	v_pk_mul_f32 v[16:17], v[20:21], v[16:17]
	v_pk_mul_f32 v[20:21], v[20:21], s[68:69] op_sel_hi:[1,0]
	v_exp_f32_e32 v28, v28
	v_exp_f32_e32 v29, v29
	v_exp_f32_e32 v20, v20
	v_exp_f32_e32 v21, v21
	v_pk_add_f32 v[32:33], v[32:33], 1.0 op_sel_hi:[1,0]
	v_pk_add_f32 v[28:29], v[28:29], 1.0 op_sel_hi:[1,0]
	v_rcp_f32_e32 v32, v32
	v_rcp_f32_e32 v33, v33
	v_pk_add_f32 v[20:21], v[20:21], 1.0 op_sel_hi:[1,0]
	v_rcp_f32_e32 v28, v28
	v_rcp_f32_e32 v29, v29
	v_rcp_f32_e32 v20, v20
	v_rcp_f32_e32 v21, v21
	v_pk_mul_f32 v[32:33], v[34:35], v[32:33]
	v_pk_mul_f32 v[26:27], v[26:27], v[28:29]
	v_cvt_pk_bf16_f32 v43, v32, v33
	v_add_u32_e32 v32, 0x90, v151
	v_mad_i64_i32 v[32:33], s[0:1], v32, s42, v[116:117]
	v_lshl_add_u64 v[32:33], v[32:33], 0, v[118:119]
	v_pk_mul_f32 v[16:17], v[16:17], v[20:21]
	global_store_dwordx4 v[32:33], v[40:43], off
	v_cvt_pk_bf16_f32 v24, v24, v25
	v_cvt_pk_bf16_f32 v25, v26, v27
	v_cvt_pk_bf16_f32 v26, v16, v17
	v_pk_mul_f32 v[16:17], v[22:23], v[138:139] op_sel_hi:[1,0]
	v_pk_mul_f32 v[18:19], v[18:19], v[138:139] op_sel_hi:[1,0]
	s_mov_b64 s[24:25], -1
	v_pk_mul_f32 v[18:19], v[16:17], v[18:19]
	v_pk_mul_f32 v[16:17], v[16:17], s[68:69] op_sel_hi:[1,0]
	s_andn2_b64 vcc, exec, s[4:5]
	v_exp_f32_e32 v16, v16
	v_exp_f32_e32 v17, v17
	s_nop 0
	v_pk_add_f32 v[16:17], v[16:17], 1.0 op_sel_hi:[1,0]
	s_nop 0
	v_rcp_f32_e32 v16, v16
	v_rcp_f32_e32 v17, v17
	s_nop 0
	v_pk_mul_f32 v[16:17], v[18:19], v[16:17]
	s_nop 0
	v_cvt_pk_bf16_f32 v27, v16, v17
	v_add_u32_e32 v16, 0xa0, v151
	v_mad_i64_i32 v[16:17], s[0:1], v16, s42, v[116:117]
	v_lshl_add_u64 v[16:17], v[16:17], 0, v[118:119]
	global_store_dwordx4 v[16:17], v[24:27], off
	s_waitcnt lgkmcnt(0)
	v_mov_b32_e32 v16, v97
	v_mov_b32_e32 v17, v98
	v_mov_b32_e32 v97, v99
	v_pk_add_f32 v[16:17], v[16:17], v[96:97]
	s_nop 0
	v_add_f32_e32 v16, v16, v17
	v_fmamk_f32 v16, v16, 0x3a800000, v229
	v_rsq_f32_e32 v16, v16
	s_nop 0
	v_pk_mul_f32 v[12:13], v[12:13], v[16:17] op_sel_hi:[1,0]
	v_pk_mul_f32 v[8:9], v[8:9], v[16:17] op_sel_hi:[1,0]
	v_pk_mul_f32 v[10:11], v[10:11], v[16:17] op_sel_hi:[1,0]
	v_pk_mul_f32 v[8:9], v[8:9], v[12:13]
	v_pk_mul_f32 v[12:13], v[12:13], s[68:69] op_sel_hi:[1,0]
	v_pk_mul_f32 v[4:5], v[4:5], v[16:17] op_sel_hi:[1,0]
	v_exp_f32_e32 v12, v12
	v_exp_f32_e32 v13, v13
	v_pk_mul_f32 v[0:1], v[0:1], v[16:17] op_sel_hi:[1,0]
	v_pk_mul_f32 v[2:3], v[2:3], v[16:17] op_sel_hi:[1,0]
	v_pk_mul_f32 v[0:1], v[4:5], v[0:1]
	v_pk_add_f32 v[12:13], v[12:13], 1.0 op_sel_hi:[1,0]
	v_pk_mul_f32 v[4:5], v[4:5], s[68:69] op_sel_hi:[1,0]
	v_rcp_f32_e32 v12, v12
	v_rcp_f32_e32 v13, v13
	v_exp_f32_e32 v4, v4
	v_exp_f32_e32 v5, v5
	v_pk_mul_f32 v[8:9], v[8:9], v[12:13]
	v_pk_mul_f32 v[12:13], v[14:15], v[16:17] op_sel_hi:[1,0]
	v_pk_add_f32 v[4:5], v[4:5], 1.0 op_sel_hi:[1,0]
	v_pk_mul_f32 v[10:11], v[12:13], v[10:11]
	v_pk_mul_f32 v[12:13], v[12:13], s[68:69] op_sel_hi:[1,0]
	v_rcp_f32_e32 v4, v4
	v_exp_f32_e32 v12, v12
	v_exp_f32_e32 v13, v13
	v_rcp_f32_e32 v5, v5
	v_cvt_pk_bf16_f32 v8, v8, v9
	v_pk_add_f32 v[12:13], v[12:13], 1.0 op_sel_hi:[1,0]
	s_nop 0
	v_rcp_f32_e32 v12, v12
	v_rcp_f32_e32 v13, v13
	v_pk_mul_f32 v[0:1], v[0:1], v[4:5]
	v_pk_mul_f32 v[10:11], v[10:11], v[12:13]
	s_nop 0
	v_cvt_pk_bf16_f32 v9, v10, v11
	v_cvt_pk_bf16_f32 v10, v0, v1
	v_pk_mul_f32 v[0:1], v[6:7], v[16:17] op_sel_hi:[1,0]
	s_nop 0
	v_pk_mul_f32 v[2:3], v[0:1], v[2:3]
	v_pk_mul_f32 v[0:1], v[0:1], s[68:69] op_sel_hi:[1,0]
	s_nop 0
	v_exp_f32_e32 v0, v0
	v_exp_f32_e32 v1, v1
	s_nop 0
	v_pk_add_f32 v[0:1], v[0:1], 1.0 op_sel_hi:[1,0]
	s_nop 0
	v_rcp_f32_e32 v0, v0
	v_rcp_f32_e32 v1, v1
	s_nop 0
	v_pk_mul_f32 v[0:1], v[2:3], v[0:1]
	s_nop 0
	v_cvt_pk_bf16_f32 v11, v0, v1
	v_add_u32_e32 v0, 0xb0, v151
	v_mad_i64_i32 v[0:1], s[0:1], v0, s42, v[116:117]
	v_lshl_add_u64 v[0:1], v[0:1], 0, v[118:119]
	global_store_dwordx4 v[0:1], v[8:11], off
	s_cbranch_vccnz .LBB0_522
	s_andn2_b64 vcc, exec, s[6:7]
	s_cbranch_vccnz .LBB0_521
	s_barrier
	s_branch .LBB0_521
